# removed the redundant s_setprio 0/1 pair in the middle of every 32-MFMA block (40 sites)
# baseline (speedup 1.0000x reference)
.LBB0_151:
	v_add_u32_e32 v14, s53, v189
	v_add_u32_e32 v168, s90, v189
	ds_read_b128 v[2:5], v14
	ds_read_b128 v[6:9], v14 offset:1024
	ds_read_b128 v[10:13], v14 offset:2048
	ds_read_b128 v[14:17], v14 offset:3072
	ds_read_b128 v[146:149], v168
	ds_read_b128 v[150:153], v168 offset:1024
	ds_read_b128 v[164:167], v168 offset:2048
	ds_read_b128 v[168:171], v168 offset:3072
	s_add_i32 s11, s6, 2
	s_add_u32 s15, s4, 0x80
	s_addc_u32 s7, s5, 0
	s_cmp_eq_u32 s46, s6
	s_cselect_b32 s6, s0, s15
	s_cselect_b32 s7, s1, s7
	s_cselect_b32 s73, s69, s10
	s_cselect_b32 s72, s68, s9
	v_lshl_add_u64 v[176:177], s[4:5], 0, v[162:163]
	s_add_i32 m0, s96, 0xc000
	ds_read_b128 v[172:175], v190
	ds_read_b128 v[182:185], v190 offset:1024
	ds_read_b128 v[192:195], v190 offset:2048
	ds_read_b128 v[196:199], v190 offset:3072
	ds_read_b128 v[218:221], v190 offset:4096
	ds_read_b128 v[222:225], v190 offset:5120
	ds_read_b128 v[230:233], v190 offset:6144
	ds_read_b128 v[234:237], v190 offset:7168
	global_load_lds_dwordx4 v[176:177], off
	v_lshl_add_u64 v[176:177], s[4:5], 0, v[160:161]
	s_add_i32 m0, s96, 0xe000
	s_nop 0
	global_load_lds_dwordx4 v[176:177], off
	s_waitcnt vmcnt(8)
	s_waitcnt lgkmcnt(0)
	s_barrier
	s_setprio 1
	s_waitcnt lgkmcnt(0)
	v_mfma_f32_16x16x32_bf16 v[138:141], v[2:5], v[172:175], v[138:141]
	v_mfma_f32_16x16x32_bf16 v[142:145], v[10:13], v[172:175], v[142:145]
	v_mfma_f32_16x16x32_bf16 v[126:129], v[2:5], v[192:195], v[126:129]
	v_mfma_f32_16x16x32_bf16 v[122:125], v[10:13], v[192:195], v[122:125]
	v_mfma_f32_16x16x32_bf16 v[110:113], v[2:5], v[218:221], v[110:113]
	v_mfma_f32_16x16x32_bf16 v[106:109], v[10:13], v[218:221], v[106:109]
	v_mfma_f32_16x16x32_bf16 v[94:97], v[2:5], v[230:233], v[94:97]
	v_mfma_f32_16x16x32_bf16 v[90:93], v[10:13], v[230:233], v[90:93]
	v_mfma_f32_16x16x32_bf16 v[138:141], v[6:9], v[182:185], v[138:141]
	v_mfma_f32_16x16x32_bf16 v[142:145], v[14:17], v[182:185], v[142:145]
	v_mfma_f32_16x16x32_bf16 v[126:129], v[6:9], v[196:199], v[126:129]
	v_mfma_f32_16x16x32_bf16 v[122:125], v[14:17], v[196:199], v[122:125]
	v_mfma_f32_16x16x32_bf16 v[110:113], v[6:9], v[222:225], v[110:113]
	v_mfma_f32_16x16x32_bf16 v[106:109], v[14:17], v[222:225], v[106:109]
	v_mfma_f32_16x16x32_bf16 v[94:97], v[6:9], v[234:237], v[94:97]
	v_mfma_f32_16x16x32_bf16 v[90:93], v[14:17], v[234:237], v[90:93]
	v_mfma_f32_16x16x32_bf16 v[134:137], v[146:149], v[172:175], v[134:137]
	v_mfma_f32_16x16x32_bf16 v[130:133], v[164:167], v[172:175], v[130:133]
	v_mfma_f32_16x16x32_bf16 v[118:121], v[146:149], v[192:195], v[118:121]
	v_mfma_f32_16x16x32_bf16 v[114:117], v[164:167], v[192:195], v[114:117]
	v_mfma_f32_16x16x32_bf16 v[102:105], v[146:149], v[218:221], v[102:105]
	v_mfma_f32_16x16x32_bf16 v[98:101], v[164:167], v[218:221], v[98:101]
	v_mfma_f32_16x16x32_bf16 v[86:89], v[146:149], v[230:233], v[86:89]
	v_mfma_f32_16x16x32_bf16 v[82:85], v[164:167], v[230:233], v[82:85]
	v_mfma_f32_16x16x32_bf16 v[134:137], v[150:153], v[182:185], v[134:137]
	v_mfma_f32_16x16x32_bf16 v[130:133], v[168:171], v[182:185], v[130:133]
	v_mfma_f32_16x16x32_bf16 v[118:121], v[150:153], v[196:199], v[118:121]
	v_mfma_f32_16x16x32_bf16 v[114:117], v[168:171], v[196:199], v[114:117]
	v_mfma_f32_16x16x32_bf16 v[102:105], v[150:153], v[222:225], v[102:105]
	v_mfma_f32_16x16x32_bf16 v[98:101], v[168:171], v[222:225], v[98:101]
	v_mfma_f32_16x16x32_bf16 v[86:89], v[150:153], v[234:237], v[86:89]
	v_mfma_f32_16x16x32_bf16 v[82:85], v[168:171], v[234:237], v[82:85]
	s_setprio 0
	s_barrier
	s_mov_b32 m0, s55
	v_lshl_add_u64 v[176:177], s[72:73], 0, v[0:1]
	v_lshl_add_u64 v[186:187], s[72:73], 0, v[158:159]
	s_add_u32 s72, s72, s20
	ds_read_b128 v[172:175], v190 offset:16384
	ds_read_b128 v[182:185], v190 offset:17408
	ds_read_b128 v[192:195], v190 offset:18432
	ds_read_b128 v[196:199], v190 offset:19456
	ds_read_b128 v[218:221], v190 offset:20480
	ds_read_b128 v[222:225], v190 offset:21504
	ds_read_b128 v[230:233], v190 offset:22528
	ds_read_b128 v[234:237], v190 offset:23552
	global_load_lds_dwordx4 v[176:177], off
	s_mov_b32 m0, s88
	s_addc_u32 s73, s73, s21
	global_load_lds_dwordx4 v[186:187], off
	v_lshl_add_u64 v[238:239], s[72:73], 0, v[0:1]
	s_mov_b32 m0, s93
	v_lshl_add_u64 v[240:241], s[72:73], 0, v[158:159]
	global_load_lds_dwordx4 v[238:239], off
	s_mov_b32 m0, s94
	v_lshl_add_u64 v[242:243], s[6:7], 0, v[154:155]
	global_load_lds_dwordx4 v[240:241], off
	s_mov_b32 m0, s96
	v_lshl_add_u64 v[244:245], s[6:7], 0, v[156:157]
	global_load_lds_dwordx4 v[242:243], off
	s_mov_b32 m0, s66
	s_nop 0
	global_load_lds_dwordx4 v[244:245], off
	s_waitcnt vmcnt(8)
	s_waitcnt lgkmcnt(0)
	s_barrier
	s_setprio 1
	s_waitcnt lgkmcnt(0)
	v_mfma_f32_16x16x32_bf16 v[78:81], v[2:5], v[172:175], v[78:81]
	v_mfma_f32_16x16x32_bf16 v[74:77], v[10:13], v[172:175], v[74:77]
	v_mfma_f32_16x16x32_bf16 v[62:65], v[2:5], v[192:195], v[62:65]
	v_mfma_f32_16x16x32_bf16 v[58:61], v[10:13], v[192:195], v[58:61]
	v_mfma_f32_16x16x32_bf16 v[46:49], v[2:5], v[218:221], v[46:49]
	v_mfma_f32_16x16x32_bf16 v[42:45], v[10:13], v[218:221], v[42:45]
	v_mfma_f32_16x16x32_bf16 v[2:5], v[2:5], v[230:233], v[30:33]
	v_mfma_f32_16x16x32_bf16 v[78:81], v[6:9], v[182:185], v[78:81]
	v_mfma_f32_16x16x32_bf16 v[74:77], v[14:17], v[182:185], v[74:77]
	v_mfma_f32_16x16x32_bf16 v[62:65], v[6:9], v[196:199], v[62:65]
	v_mfma_f32_16x16x32_bf16 v[58:61], v[14:17], v[196:199], v[58:61]
	v_mfma_f32_16x16x32_bf16 v[46:49], v[6:9], v[222:225], v[46:49]
	v_mfma_f32_16x16x32_bf16 v[42:45], v[14:17], v[222:225], v[42:45]
	v_mfma_f32_16x16x32_bf16 v[2:5], v[6:9], v[234:237], v[2:5]
	v_mfma_f32_16x16x32_bf16 v[6:9], v[10:13], v[230:233], v[26:29]
	v_mfma_f32_16x16x32_bf16 v[6:9], v[14:17], v[234:237], v[6:9]
	v_mfma_f32_16x16x32_bf16 v[26:29], v[146:149], v[192:195], v[54:57]
	v_mfma_f32_16x16x32_bf16 v[54:57], v[150:153], v[196:199], v[26:29]
	v_mfma_f32_16x16x32_bf16 v[26:29], v[164:167], v[192:195], v[50:53]
	v_mfma_f32_16x16x32_bf16 v[50:53], v[168:171], v[196:199], v[26:29]
	v_mfma_f32_16x16x32_bf16 v[26:29], v[146:149], v[218:221], v[38:41]
	v_mfma_f32_16x16x32_bf16 v[38:41], v[150:153], v[222:225], v[26:29]
	v_mfma_f32_16x16x32_bf16 v[26:29], v[164:167], v[218:221], v[34:37]
	v_mfma_f32_16x16x32_bf16 v[22:25], v[146:149], v[230:233], v[22:25]
	v_mfma_f32_16x16x32_bf16 v[18:21], v[164:167], v[230:233], v[18:21]
	v_mfma_f32_16x16x32_bf16 v[10:13], v[146:149], v[172:175], v[70:73]
	v_mfma_f32_16x16x32_bf16 v[14:17], v[164:167], v[172:175], v[66:69]
	v_mfma_f32_16x16x32_bf16 v[34:37], v[168:171], v[222:225], v[26:29]
	v_mfma_f32_16x16x32_bf16 v[22:25], v[150:153], v[234:237], v[22:25]
	v_mfma_f32_16x16x32_bf16 v[18:21], v[168:171], v[234:237], v[18:21]
	v_mfma_f32_16x16x32_bf16 v[10:13], v[150:153], v[182:185], v[10:13]
	v_mfma_f32_16x16x32_bf16 v[14:17], v[168:171], v[182:185], v[14:17]
	s_setprio 0
	s_barrier
	v_add_u32_e32 v70, s16, v189
	v_add_u32_e32 v168, s52, v189
	ds_read_b128 v[26:29], v70
	ds_read_b128 v[30:33], v70 offset:1024
	ds_read_b128 v[66:69], v70 offset:2048
	ds_read_b128 v[70:73], v70 offset:3072
	ds_read_b128 v[146:149], v168
	ds_read_b128 v[150:153], v168 offset:1024
	ds_read_b128 v[164:167], v168 offset:2048
	ds_read_b128 v[168:171], v168 offset:3072
	s_add_u32 s6, s6, s18
	s_addc_u32 s7, s7, s19
	s_mov_b32 m0, s67
	v_lshl_add_u64 v[246:247], s[6:7], 0, v[154:155]
	ds_read_b128 v[172:175], v190 offset:32768
	ds_read_b128 v[182:185], v190 offset:33792
	ds_read_b128 v[192:195], v190 offset:34816
	ds_read_b128 v[196:199], v190 offset:35840
	ds_read_b128 v[218:221], v190 offset:36864
	ds_read_b128 v[222:225], v190 offset:37888
	ds_read_b128 v[230:233], v190 offset:38912
	ds_read_b128 v[234:237], v190 offset:39936
	global_load_lds_dwordx4 v[246:247], off
	v_lshl_add_u64 v[246:247], s[6:7], 0, v[156:157]
	s_mov_b32 m0, s47
	s_nop 0
	global_load_lds_dwordx4 v[246:247], off
	s_waitcnt vmcnt(8)
	s_waitcnt lgkmcnt(0)
	s_barrier
	s_setprio 1
	s_waitcnt lgkmcnt(0)
	v_mfma_f32_16x16x32_bf16 v[138:141], v[26:29], v[172:175], v[138:141]
	v_mfma_f32_16x16x32_bf16 v[142:145], v[66:69], v[172:175], v[142:145]
	v_mfma_f32_16x16x32_bf16 v[126:129], v[26:29], v[192:195], v[126:129]
	v_mfma_f32_16x16x32_bf16 v[122:125], v[66:69], v[192:195], v[122:125]
	v_mfma_f32_16x16x32_bf16 v[110:113], v[26:29], v[218:221], v[110:113]
	v_mfma_f32_16x16x32_bf16 v[106:109], v[66:69], v[218:221], v[106:109]
	v_mfma_f32_16x16x32_bf16 v[94:97], v[26:29], v[230:233], v[94:97]
	v_mfma_f32_16x16x32_bf16 v[90:93], v[66:69], v[230:233], v[90:93]
	v_mfma_f32_16x16x32_bf16 v[138:141], v[30:33], v[182:185], v[138:141]
	v_mfma_f32_16x16x32_bf16 v[142:145], v[70:73], v[182:185], v[142:145]
	v_mfma_f32_16x16x32_bf16 v[126:129], v[30:33], v[196:199], v[126:129]
	v_mfma_f32_16x16x32_bf16 v[122:125], v[70:73], v[196:199], v[122:125]
	v_mfma_f32_16x16x32_bf16 v[110:113], v[30:33], v[222:225], v[110:113]
	v_mfma_f32_16x16x32_bf16 v[106:109], v[70:73], v[222:225], v[106:109]
	v_mfma_f32_16x16x32_bf16 v[94:97], v[30:33], v[234:237], v[94:97]
	v_mfma_f32_16x16x32_bf16 v[90:93], v[70:73], v[234:237], v[90:93]
	v_mfma_f32_16x16x32_bf16 v[134:137], v[146:149], v[172:175], v[134:137]
	v_mfma_f32_16x16x32_bf16 v[130:133], v[164:167], v[172:175], v[130:133]
	v_mfma_f32_16x16x32_bf16 v[118:121], v[146:149], v[192:195], v[118:121]
	v_mfma_f32_16x16x32_bf16 v[114:117], v[164:167], v[192:195], v[114:117]
	v_mfma_f32_16x16x32_bf16 v[102:105], v[146:149], v[218:221], v[102:105]
	v_mfma_f32_16x16x32_bf16 v[98:101], v[164:167], v[218:221], v[98:101]
	v_mfma_f32_16x16x32_bf16 v[86:89], v[146:149], v[230:233], v[86:89]
	v_mfma_f32_16x16x32_bf16 v[82:85], v[164:167], v[230:233], v[82:85]
	v_mfma_f32_16x16x32_bf16 v[134:137], v[150:153], v[182:185], v[134:137]
	v_mfma_f32_16x16x32_bf16 v[130:133], v[168:171], v[182:185], v[130:133]
	v_mfma_f32_16x16x32_bf16 v[118:121], v[150:153], v[196:199], v[118:121]
	v_mfma_f32_16x16x32_bf16 v[114:117], v[168:171], v[196:199], v[114:117]
	v_mfma_f32_16x16x32_bf16 v[102:105], v[150:153], v[222:225], v[102:105]
	v_mfma_f32_16x16x32_bf16 v[98:101], v[168:171], v[222:225], v[98:101]
	v_mfma_f32_16x16x32_bf16 v[86:89], v[150:153], v[234:237], v[86:89]
	v_mfma_f32_16x16x32_bf16 v[82:85], v[168:171], v[234:237], v[82:85]
	s_setprio 0
	s_barrier
	s_mov_b32 m0, s91
	v_lshl_add_u64 v[176:177], v[176:177], 0, s[48:49]
	ds_read_b128 v[172:175], v190 offset:49152
	ds_read_b128 v[182:185], v190 offset:50176
	ds_read_b128 v[192:195], v190 offset:51200
	ds_read_b128 v[196:199], v190 offset:52224
	ds_read_b128 v[218:221], v190 offset:53248
	ds_read_b128 v[222:225], v190 offset:54272
	ds_read_b128 v[230:233], v190 offset:55296
	ds_read_b128 v[234:237], v190 offset:56320
	global_load_lds_dwordx4 v[176:177], off
	v_lshl_add_u64 v[176:177], v[186:187], 0, s[48:49]
	s_mov_b32 m0, s64
	s_nop 0
	global_load_lds_dwordx4 v[176:177], off
	v_lshl_add_u64 v[176:177], v[238:239], 0, s[48:49]
	s_mov_b32 m0, s89
	s_nop 0
	global_load_lds_dwordx4 v[176:177], off
	v_lshl_add_u64 v[176:177], v[240:241], 0, s[48:49]
	s_mov_b32 m0, s70
	s_nop 0
	global_load_lds_dwordx4 v[176:177], off
	v_lshl_add_u64 v[176:177], v[242:243], 0, s[48:49]
	s_mov_b32 m0, s65
	s_nop 0
	global_load_lds_dwordx4 v[176:177], off
	v_lshl_add_u64 v[176:177], v[244:245], 0, s[48:49]
	s_mov_b32 m0, s87
	s_nop 0
	global_load_lds_dwordx4 v[176:177], off
	s_waitcnt vmcnt(8)
	s_waitcnt lgkmcnt(0)
	s_barrier
	s_setprio 1
	s_waitcnt lgkmcnt(0)
	v_mfma_f32_16x16x32_bf16 v[78:81], v[26:29], v[172:175], v[78:81]
	v_mfma_f32_16x16x32_bf16 v[62:65], v[26:29], v[192:195], v[62:65]
	v_mfma_f32_16x16x32_bf16 v[46:49], v[26:29], v[218:221], v[46:49]
	v_mfma_f32_16x16x32_bf16 v[2:5], v[26:29], v[230:233], v[2:5]
	v_mfma_f32_16x16x32_bf16 v[78:81], v[30:33], v[182:185], v[78:81]
	v_mfma_f32_16x16x32_bf16 v[74:77], v[66:69], v[172:175], v[74:77]
	v_mfma_f32_16x16x32_bf16 v[62:65], v[30:33], v[196:199], v[62:65]
	v_mfma_f32_16x16x32_bf16 v[58:61], v[66:69], v[192:195], v[58:61]
	v_mfma_f32_16x16x32_bf16 v[46:49], v[30:33], v[222:225], v[46:49]
	v_mfma_f32_16x16x32_bf16 v[42:45], v[66:69], v[218:221], v[42:45]
	v_mfma_f32_16x16x32_bf16 v[30:33], v[30:33], v[234:237], v[2:5]
	v_mfma_f32_16x16x32_bf16 v[2:5], v[66:69], v[230:233], v[6:9]
	v_mfma_f32_16x16x32_bf16 v[74:77], v[70:73], v[182:185], v[74:77]
	v_mfma_f32_16x16x32_bf16 v[58:61], v[70:73], v[196:199], v[58:61]
	v_mfma_f32_16x16x32_bf16 v[42:45], v[70:73], v[222:225], v[42:45]
	v_mfma_f32_16x16x32_bf16 v[26:29], v[70:73], v[234:237], v[2:5]
	v_mfma_f32_16x16x32_bf16 v[2:5], v[146:149], v[172:175], v[10:13]
	v_mfma_f32_16x16x32_bf16 v[70:73], v[150:153], v[182:185], v[2:5]
	v_mfma_f32_16x16x32_bf16 v[2:5], v[164:167], v[172:175], v[14:17]
	v_mfma_f32_16x16x32_bf16 v[66:69], v[168:171], v[182:185], v[2:5]
	v_mfma_f32_16x16x32_bf16 v[2:5], v[146:149], v[192:195], v[54:57]
	v_mfma_f32_16x16x32_bf16 v[54:57], v[150:153], v[196:199], v[2:5]
	v_mfma_f32_16x16x32_bf16 v[2:5], v[164:167], v[192:195], v[50:53]
	v_mfma_f32_16x16x32_bf16 v[50:53], v[168:171], v[196:199], v[2:5]
	v_mfma_f32_16x16x32_bf16 v[2:5], v[146:149], v[218:221], v[38:41]
	v_mfma_f32_16x16x32_bf16 v[38:41], v[150:153], v[222:225], v[2:5]
	v_mfma_f32_16x16x32_bf16 v[2:5], v[164:167], v[218:221], v[34:37]
	v_mfma_f32_16x16x32_bf16 v[34:37], v[168:171], v[222:225], v[2:5]
	v_mfma_f32_16x16x32_bf16 v[2:5], v[146:149], v[230:233], v[22:25]
	v_mfma_f32_16x16x32_bf16 v[22:25], v[150:153], v[234:237], v[2:5]
	v_mfma_f32_16x16x32_bf16 v[2:5], v[164:167], v[230:233], v[18:21]
	v_mfma_f32_16x16x32_bf16 v[18:21], v[168:171], v[234:237], v[2:5]
	s_setprio 0
	s_barrier
	s_add_u32 s9, s9, 0x100
	s_addc_u32 s10, s10, 0
	s_add_u32 s4, s4, 0x100
	s_addc_u32 s5, s5, 0
	s_cmp_ge_i32 s11, s86
	s_mov_b32 s6, s11
	s_cbranch_scc0 .LBB0_151

.LBB0_662:
	v_add_u32_e32 v152, s47, v156
	ds_read_b128 v[130:133], v152
	ds_read_b128 v[134:137], v152 offset:1024
	ds_read_b128 v[148:151], v152 offset:2048
	ds_read_b128 v[158:161], v152 offset:3072
	v_add_u32_e32 v152, s52, v156
	ds_read_b128 v[162:165], v152
	ds_read_b128 v[166:169], v152 offset:1024
	ds_read_b128 v[170:173], v152 offset:2048
	ds_read_b128 v[174:177], v152 offset:3072
	s_add_i32 s34, s28, 2
	s_add_u32 s35, s4, 0x80
	s_addc_u32 s29, s5, 0
	s_cmp_eq_u32 s75, s28
	s_cselect_b32 s28, s0, s35
	s_cselect_b32 s29, s1, s29
	s_cselect_b32 s71, s27, s31
	s_cselect_b32 s70, s26, s30
	v_lshl_add_u64 v[152:153], s[4:5], 0, v[146:147]
	s_add_i32 m0, s55, 0xc000
	ds_read_b128 v[182:185], v157
	ds_read_b128 v[186:189], v157 offset:1024
	ds_read_b128 v[190:193], v157 offset:2048
	ds_read_b128 v[194:197], v157 offset:3072
	ds_read_b128 v[218:221], v157 offset:4096
	ds_read_b128 v[222:225], v157 offset:5120
	ds_read_b128 v[230:233], v157 offset:6144
	ds_read_b128 v[234:237], v157 offset:7168
	global_load_lds_dwordx4 v[152:153], off
	v_lshl_add_u64 v[152:153], s[4:5], 0, v[144:145]
	s_add_i32 m0, s55, 0xe000
	s_nop 0
	global_load_lds_dwordx4 v[152:153], off
	s_waitcnt vmcnt(8)
	s_waitcnt lgkmcnt(0)
	s_barrier
	s_setprio 1
	s_waitcnt lgkmcnt(0)
	v_mfma_f32_16x16x32_bf16 v[6:9], v[130:133], v[182:185], v[6:9]
	v_mfma_f32_16x16x32_bf16 v[2:5], v[148:151], v[182:185], v[2:5]
	v_mfma_f32_16x16x32_bf16 v[126:129], v[130:133], v[190:193], v[126:129]
	v_mfma_f32_16x16x32_bf16 v[122:125], v[148:151], v[190:193], v[122:125]
	v_mfma_f32_16x16x32_bf16 v[118:121], v[130:133], v[218:221], v[118:121]
	v_mfma_f32_16x16x32_bf16 v[114:117], v[148:151], v[218:221], v[114:117]
	v_mfma_f32_16x16x32_bf16 v[110:113], v[130:133], v[230:233], v[110:113]
	v_mfma_f32_16x16x32_bf16 v[106:109], v[148:151], v[230:233], v[106:109]
	v_mfma_f32_16x16x32_bf16 v[6:9], v[134:137], v[186:189], v[6:9]
	v_mfma_f32_16x16x32_bf16 v[2:5], v[158:161], v[186:189], v[2:5]
	v_mfma_f32_16x16x32_bf16 v[126:129], v[134:137], v[194:197], v[126:129]
	v_mfma_f32_16x16x32_bf16 v[122:125], v[158:161], v[194:197], v[122:125]
	v_mfma_f32_16x16x32_bf16 v[118:121], v[134:137], v[222:225], v[118:121]
	v_mfma_f32_16x16x32_bf16 v[114:117], v[158:161], v[222:225], v[114:117]
	v_mfma_f32_16x16x32_bf16 v[110:113], v[134:137], v[234:237], v[110:113]
	v_mfma_f32_16x16x32_bf16 v[106:109], v[158:161], v[234:237], v[106:109]
	v_mfma_f32_16x16x32_bf16 v[70:73], v[162:165], v[182:185], v[70:73]
	v_mfma_f32_16x16x32_bf16 v[66:69], v[170:173], v[182:185], v[66:69]
	v_mfma_f32_16x16x32_bf16 v[62:65], v[162:165], v[190:193], v[62:65]
	v_mfma_f32_16x16x32_bf16 v[58:61], v[170:173], v[190:193], v[58:61]
	v_mfma_f32_16x16x32_bf16 v[54:57], v[162:165], v[218:221], v[54:57]
	v_mfma_f32_16x16x32_bf16 v[50:53], v[170:173], v[218:221], v[50:53]
	v_mfma_f32_16x16x32_bf16 v[46:49], v[162:165], v[230:233], v[46:49]
	v_mfma_f32_16x16x32_bf16 v[42:45], v[170:173], v[230:233], v[42:45]
	v_mfma_f32_16x16x32_bf16 v[70:73], v[166:169], v[186:189], v[70:73]
	v_mfma_f32_16x16x32_bf16 v[66:69], v[174:177], v[186:189], v[66:69]
	v_mfma_f32_16x16x32_bf16 v[62:65], v[166:169], v[194:197], v[62:65]
	v_mfma_f32_16x16x32_bf16 v[58:61], v[174:177], v[194:197], v[58:61]
	v_mfma_f32_16x16x32_bf16 v[54:57], v[166:169], v[222:225], v[54:57]
	v_mfma_f32_16x16x32_bf16 v[50:53], v[174:177], v[222:225], v[50:53]
	v_mfma_f32_16x16x32_bf16 v[46:49], v[166:169], v[234:237], v[46:49]
	v_mfma_f32_16x16x32_bf16 v[42:45], v[174:177], v[234:237], v[42:45]
	s_setprio 0
	s_barrier
	s_mov_b32 m0, s50
	v_lshl_add_u64 v[152:153], s[70:71], 0, v[0:1]
	v_lshl_add_u64 v[198:199], s[70:71], 0, v[142:143]
	s_add_u32 s70, s70, s10
	ds_read_b128 v[182:185], v157 offset:16384
	ds_read_b128 v[186:189], v157 offset:17408
	ds_read_b128 v[190:193], v157 offset:18432
	ds_read_b128 v[194:197], v157 offset:19456
	ds_read_b128 v[218:221], v157 offset:20480
	ds_read_b128 v[222:225], v157 offset:21504
	ds_read_b128 v[230:233], v157 offset:22528
	ds_read_b128 v[234:237], v157 offset:23552
	global_load_lds_dwordx4 v[152:153], off
	s_mov_b32 m0, s51
	s_addc_u32 s71, s71, s11
	global_load_lds_dwordx4 v[198:199], off
	v_lshl_add_u64 v[238:239], s[70:71], 0, v[0:1]
	s_mov_b32 m0, s53
	v_lshl_add_u64 v[240:241], s[70:71], 0, v[142:143]
	global_load_lds_dwordx4 v[238:239], off
	s_mov_b32 m0, s54
	v_lshl_add_u64 v[242:243], s[28:29], 0, v[138:139]
	global_load_lds_dwordx4 v[240:241], off
	s_mov_b32 m0, s55
	v_lshl_add_u64 v[244:245], s[28:29], 0, v[140:141]
	global_load_lds_dwordx4 v[242:243], off
	s_mov_b32 m0, s58
	s_nop 0
	global_load_lds_dwordx4 v[244:245], off
	s_waitcnt vmcnt(8)
	s_waitcnt lgkmcnt(0)
	s_barrier
	s_setprio 1
	s_waitcnt lgkmcnt(0)
	v_mfma_f32_16x16x32_bf16 v[102:105], v[130:133], v[182:185], v[102:105]
	v_mfma_f32_16x16x32_bf16 v[98:101], v[148:151], v[182:185], v[98:101]
	v_mfma_f32_16x16x32_bf16 v[94:97], v[130:133], v[190:193], v[94:97]
	v_mfma_f32_16x16x32_bf16 v[90:93], v[148:151], v[190:193], v[90:93]
	v_mfma_f32_16x16x32_bf16 v[86:89], v[130:133], v[218:221], v[86:89]
	v_mfma_f32_16x16x32_bf16 v[82:85], v[148:151], v[218:221], v[82:85]
	v_mfma_f32_16x16x32_bf16 v[78:81], v[130:133], v[230:233], v[78:81]
	v_mfma_f32_16x16x32_bf16 v[74:77], v[148:151], v[230:233], v[74:77]
	v_mfma_f32_16x16x32_bf16 v[102:105], v[134:137], v[186:189], v[102:105]
	v_mfma_f32_16x16x32_bf16 v[98:101], v[158:161], v[186:189], v[98:101]
	v_mfma_f32_16x16x32_bf16 v[94:97], v[134:137], v[194:197], v[94:97]
	v_mfma_f32_16x16x32_bf16 v[90:93], v[158:161], v[194:197], v[90:93]
	v_mfma_f32_16x16x32_bf16 v[86:89], v[134:137], v[222:225], v[86:89]
	v_mfma_f32_16x16x32_bf16 v[82:85], v[158:161], v[222:225], v[82:85]
	v_mfma_f32_16x16x32_bf16 v[78:81], v[134:137], v[234:237], v[78:81]
	v_mfma_f32_16x16x32_bf16 v[74:77], v[158:161], v[234:237], v[74:77]
	v_mfma_f32_16x16x32_bf16 v[38:41], v[162:165], v[182:185], v[38:41]
	v_mfma_f32_16x16x32_bf16 v[34:37], v[170:173], v[182:185], v[34:37]
	v_mfma_f32_16x16x32_bf16 v[30:33], v[162:165], v[190:193], v[30:33]
	v_mfma_f32_16x16x32_bf16 v[26:29], v[170:173], v[190:193], v[26:29]
	v_mfma_f32_16x16x32_bf16 v[22:25], v[162:165], v[218:221], v[22:25]
	v_mfma_f32_16x16x32_bf16 v[18:21], v[170:173], v[218:221], v[18:21]
	v_mfma_f32_16x16x32_bf16 v[14:17], v[162:165], v[230:233], v[14:17]
	v_mfma_f32_16x16x32_bf16 v[10:13], v[170:173], v[230:233], v[10:13]
	v_mfma_f32_16x16x32_bf16 v[38:41], v[166:169], v[186:189], v[38:41]
	v_mfma_f32_16x16x32_bf16 v[34:37], v[174:177], v[186:189], v[34:37]
	v_mfma_f32_16x16x32_bf16 v[30:33], v[166:169], v[194:197], v[30:33]
	v_mfma_f32_16x16x32_bf16 v[26:29], v[174:177], v[194:197], v[26:29]
	v_mfma_f32_16x16x32_bf16 v[22:25], v[166:169], v[222:225], v[22:25]
	v_mfma_f32_16x16x32_bf16 v[18:21], v[174:177], v[222:225], v[18:21]
	v_mfma_f32_16x16x32_bf16 v[14:17], v[166:169], v[234:237], v[14:17]
	v_mfma_f32_16x16x32_bf16 v[10:13], v[174:177], v[234:237], v[10:13]
	s_setprio 0
	s_barrier
	v_add_u32_e32 v158, s63, v156
	v_add_u32_e32 v174, s72, v156
	ds_read_b128 v[130:133], v158
	ds_read_b128 v[134:137], v158 offset:1024
	ds_read_b128 v[148:151], v158 offset:2048
	ds_read_b128 v[158:161], v158 offset:3072
	ds_read_b128 v[162:165], v174
	ds_read_b128 v[166:169], v174 offset:1024
	ds_read_b128 v[170:173], v174 offset:2048
	ds_read_b128 v[174:177], v174 offset:3072
	s_add_u32 s28, s28, s8
	s_addc_u32 s29, s29, s9
	s_mov_b32 m0, s59
	v_lshl_add_u64 v[246:247], s[28:29], 0, v[138:139]
	ds_read_b128 v[182:185], v157 offset:32768
	ds_read_b128 v[186:189], v157 offset:33792
	ds_read_b128 v[190:193], v157 offset:34816
	ds_read_b128 v[194:197], v157 offset:35840
	ds_read_b128 v[218:221], v157 offset:36864
	ds_read_b128 v[222:225], v157 offset:37888
	ds_read_b128 v[230:233], v157 offset:38912
	ds_read_b128 v[234:237], v157 offset:39936
	global_load_lds_dwordx4 v[246:247], off
	v_lshl_add_u64 v[246:247], s[28:29], 0, v[140:141]
	s_mov_b32 m0, s60
	s_nop 0
	global_load_lds_dwordx4 v[246:247], off
	s_waitcnt vmcnt(8)
	s_waitcnt lgkmcnt(0)
	s_barrier
	s_setprio 1
	s_waitcnt lgkmcnt(0)
	v_mfma_f32_16x16x32_bf16 v[6:9], v[130:133], v[182:185], v[6:9]
	v_mfma_f32_16x16x32_bf16 v[2:5], v[148:151], v[182:185], v[2:5]
	v_mfma_f32_16x16x32_bf16 v[126:129], v[130:133], v[190:193], v[126:129]
	v_mfma_f32_16x16x32_bf16 v[122:125], v[148:151], v[190:193], v[122:125]
	v_mfma_f32_16x16x32_bf16 v[118:121], v[130:133], v[218:221], v[118:121]
	v_mfma_f32_16x16x32_bf16 v[114:117], v[148:151], v[218:221], v[114:117]
	v_mfma_f32_16x16x32_bf16 v[110:113], v[130:133], v[230:233], v[110:113]
	v_mfma_f32_16x16x32_bf16 v[106:109], v[148:151], v[230:233], v[106:109]
	v_mfma_f32_16x16x32_bf16 v[6:9], v[134:137], v[186:189], v[6:9]
	v_mfma_f32_16x16x32_bf16 v[2:5], v[158:161], v[186:189], v[2:5]
	v_mfma_f32_16x16x32_bf16 v[126:129], v[134:137], v[194:197], v[126:129]
	v_mfma_f32_16x16x32_bf16 v[122:125], v[158:161], v[194:197], v[122:125]
	v_mfma_f32_16x16x32_bf16 v[118:121], v[134:137], v[222:225], v[118:121]
	v_mfma_f32_16x16x32_bf16 v[114:117], v[158:161], v[222:225], v[114:117]
	v_mfma_f32_16x16x32_bf16 v[110:113], v[134:137], v[234:237], v[110:113]
	v_mfma_f32_16x16x32_bf16 v[106:109], v[158:161], v[234:237], v[106:109]
	v_mfma_f32_16x16x32_bf16 v[70:73], v[162:165], v[182:185], v[70:73]
	v_mfma_f32_16x16x32_bf16 v[66:69], v[170:173], v[182:185], v[66:69]
	v_mfma_f32_16x16x32_bf16 v[62:65], v[162:165], v[190:193], v[62:65]
	v_mfma_f32_16x16x32_bf16 v[58:61], v[170:173], v[190:193], v[58:61]
	v_mfma_f32_16x16x32_bf16 v[54:57], v[162:165], v[218:221], v[54:57]
	v_mfma_f32_16x16x32_bf16 v[50:53], v[170:173], v[218:221], v[50:53]
	v_mfma_f32_16x16x32_bf16 v[46:49], v[162:165], v[230:233], v[46:49]
	v_mfma_f32_16x16x32_bf16 v[42:45], v[170:173], v[230:233], v[42:45]
	v_mfma_f32_16x16x32_bf16 v[70:73], v[166:169], v[186:189], v[70:73]
	v_mfma_f32_16x16x32_bf16 v[66:69], v[174:177], v[186:189], v[66:69]
	v_mfma_f32_16x16x32_bf16 v[62:65], v[166:169], v[194:197], v[62:65]
	v_mfma_f32_16x16x32_bf16 v[58:61], v[174:177], v[194:197], v[58:61]
	v_mfma_f32_16x16x32_bf16 v[54:57], v[166:169], v[222:225], v[54:57]
	v_mfma_f32_16x16x32_bf16 v[50:53], v[174:177], v[222:225], v[50:53]
	v_mfma_f32_16x16x32_bf16 v[46:49], v[166:169], v[234:237], v[46:49]
	v_mfma_f32_16x16x32_bf16 v[42:45], v[174:177], v[234:237], v[42:45]
	s_setprio 0
	s_barrier
	s_mov_b32 m0, s64
	v_lshl_add_u64 v[152:153], v[152:153], 0, s[48:49]
	ds_read_b128 v[182:185], v157 offset:49152
	ds_read_b128 v[186:189], v157 offset:50176
	ds_read_b128 v[190:193], v157 offset:51200
	ds_read_b128 v[194:197], v157 offset:52224
	ds_read_b128 v[218:221], v157 offset:53248
	ds_read_b128 v[222:225], v157 offset:54272
	ds_read_b128 v[230:233], v157 offset:55296
	ds_read_b128 v[234:237], v157 offset:56320
	global_load_lds_dwordx4 v[152:153], off
	v_lshl_add_u64 v[152:153], v[198:199], 0, s[48:49]
	s_mov_b32 m0, s65
	s_nop 0
	global_load_lds_dwordx4 v[152:153], off
	v_lshl_add_u64 v[152:153], v[238:239], 0, s[48:49]
	s_mov_b32 m0, s73
	s_nop 0
	global_load_lds_dwordx4 v[152:153], off
	v_lshl_add_u64 v[152:153], v[240:241], 0, s[48:49]
	s_mov_b32 m0, s74
	s_nop 0
	global_load_lds_dwordx4 v[152:153], off
	v_lshl_add_u64 v[152:153], v[242:243], 0, s[48:49]
	s_mov_b32 m0, s66
	s_nop 0
	global_load_lds_dwordx4 v[152:153], off
	v_lshl_add_u64 v[152:153], v[244:245], 0, s[48:49]
	s_mov_b32 m0, s67
	s_nop 0
	global_load_lds_dwordx4 v[152:153], off
	s_waitcnt vmcnt(8)
	s_waitcnt lgkmcnt(0)
	s_barrier
	s_setprio 1
	s_waitcnt lgkmcnt(0)
	v_mfma_f32_16x16x32_bf16 v[102:105], v[130:133], v[182:185], v[102:105]
	v_mfma_f32_16x16x32_bf16 v[98:101], v[148:151], v[182:185], v[98:101]
	v_mfma_f32_16x16x32_bf16 v[94:97], v[130:133], v[190:193], v[94:97]
	v_mfma_f32_16x16x32_bf16 v[90:93], v[148:151], v[190:193], v[90:93]
	v_mfma_f32_16x16x32_bf16 v[86:89], v[130:133], v[218:221], v[86:89]
	v_mfma_f32_16x16x32_bf16 v[82:85], v[148:151], v[218:221], v[82:85]
	v_mfma_f32_16x16x32_bf16 v[78:81], v[130:133], v[230:233], v[78:81]
	v_mfma_f32_16x16x32_bf16 v[74:77], v[148:151], v[230:233], v[74:77]
	v_mfma_f32_16x16x32_bf16 v[102:105], v[134:137], v[186:189], v[102:105]
	v_mfma_f32_16x16x32_bf16 v[98:101], v[158:161], v[186:189], v[98:101]
	v_mfma_f32_16x16x32_bf16 v[94:97], v[134:137], v[194:197], v[94:97]
	v_mfma_f32_16x16x32_bf16 v[90:93], v[158:161], v[194:197], v[90:93]
	v_mfma_f32_16x16x32_bf16 v[86:89], v[134:137], v[222:225], v[86:89]
	v_mfma_f32_16x16x32_bf16 v[82:85], v[158:161], v[222:225], v[82:85]
	v_mfma_f32_16x16x32_bf16 v[78:81], v[134:137], v[234:237], v[78:81]
	v_mfma_f32_16x16x32_bf16 v[74:77], v[158:161], v[234:237], v[74:77]
	v_mfma_f32_16x16x32_bf16 v[38:41], v[162:165], v[182:185], v[38:41]
	v_mfma_f32_16x16x32_bf16 v[34:37], v[170:173], v[182:185], v[34:37]
	v_mfma_f32_16x16x32_bf16 v[30:33], v[162:165], v[190:193], v[30:33]
	v_mfma_f32_16x16x32_bf16 v[26:29], v[170:173], v[190:193], v[26:29]
	v_mfma_f32_16x16x32_bf16 v[22:25], v[162:165], v[218:221], v[22:25]
	v_mfma_f32_16x16x32_bf16 v[18:21], v[170:173], v[218:221], v[18:21]
	v_mfma_f32_16x16x32_bf16 v[14:17], v[162:165], v[230:233], v[14:17]
	v_mfma_f32_16x16x32_bf16 v[10:13], v[170:173], v[230:233], v[10:13]
	v_mfma_f32_16x16x32_bf16 v[38:41], v[166:169], v[186:189], v[38:41]
	v_mfma_f32_16x16x32_bf16 v[34:37], v[174:177], v[186:189], v[34:37]
	v_mfma_f32_16x16x32_bf16 v[30:33], v[166:169], v[194:197], v[30:33]
	v_mfma_f32_16x16x32_bf16 v[26:29], v[174:177], v[194:197], v[26:29]
	v_mfma_f32_16x16x32_bf16 v[22:25], v[166:169], v[222:225], v[22:25]
	v_mfma_f32_16x16x32_bf16 v[18:21], v[174:177], v[222:225], v[18:21]
	v_mfma_f32_16x16x32_bf16 v[14:17], v[166:169], v[234:237], v[14:17]
	v_mfma_f32_16x16x32_bf16 v[10:13], v[174:177], v[234:237], v[10:13]
	s_setprio 0
	s_barrier
	s_add_u32 s30, s30, 0x100
	s_addc_u32 s31, s31, 0
	s_add_u32 s4, s4, 0x100
	s_addc_u32 s5, s5, 0
	s_cmp_ge_i32 s34, s62
	s_mov_b32 s28, s34
	s_cbranch_scc0 .LBB0_662

.LBB0_763:
	v_add_u32_e32 v156, s34, v150
	v_add_u32_e32 v172, s44, v150
	ds_read_b128 v[140:143], v156
	ds_read_b128 v[144:147], v156 offset:1024
	ds_read_b128 v[152:155], v156 offset:2048
	ds_read_b128 v[156:159], v156 offset:3072
	ds_read_b128 v[160:163], v172
	ds_read_b128 v[164:167], v172 offset:1024
	ds_read_b128 v[168:171], v172 offset:2048
	ds_read_b128 v[172:175], v172 offset:3072
	s_add_i32 s83, s28, 2
	s_add_u32 s84, s4, 0x80
	s_addc_u32 s29, s5, 0
	s_cmp_eq_u32 s70, s28
	s_cselect_b32 s28, s0, s84
	s_cselect_b32 s29, s1, s29
	s_cselect_b32 s85, s27, s82
	s_cselect_b32 s84, s26, s81
	v_lshl_add_u64 v[176:177], s[4:5], 0, v[138:139]
	s_add_i32 m0, s50, 0xc000
	ds_read_b128 v[182:185], v151
	ds_read_b128 v[186:189], v151 offset:1024
	ds_read_b128 v[190:193], v151 offset:2048
	ds_read_b128 v[194:197], v151 offset:3072
	ds_read_b128 v[218:221], v151 offset:4096
	ds_read_b128 v[222:225], v151 offset:5120
	ds_read_b128 v[230:233], v151 offset:6144
	ds_read_b128 v[234:237], v151 offset:7168
	global_load_lds_dwordx4 v[176:177], off
	v_lshl_add_u64 v[176:177], s[4:5], 0, v[136:137]
	s_add_i32 m0, s50, 0xe000
	s_nop 0
	global_load_lds_dwordx4 v[176:177], off
	s_waitcnt vmcnt(8)
	s_waitcnt lgkmcnt(0)
	s_barrier
	s_setprio 1
	s_waitcnt lgkmcnt(0)
	v_mfma_f32_16x16x32_bf16 v[122:125], v[140:143], v[182:185], v[122:125]
	v_mfma_f32_16x16x32_bf16 v[126:129], v[152:155], v[182:185], v[126:129]
	v_mfma_f32_16x16x32_bf16 v[110:113], v[140:143], v[190:193], v[110:113]
	v_mfma_f32_16x16x32_bf16 v[106:109], v[152:155], v[190:193], v[106:109]
	v_mfma_f32_16x16x32_bf16 v[94:97], v[140:143], v[218:221], v[94:97]
	v_mfma_f32_16x16x32_bf16 v[90:93], v[152:155], v[218:221], v[90:93]
	v_mfma_f32_16x16x32_bf16 v[78:81], v[140:143], v[230:233], v[78:81]
	v_mfma_f32_16x16x32_bf16 v[74:77], v[152:155], v[230:233], v[74:77]
	v_mfma_f32_16x16x32_bf16 v[122:125], v[144:147], v[186:189], v[122:125]
	v_mfma_f32_16x16x32_bf16 v[126:129], v[156:159], v[186:189], v[126:129]
	v_mfma_f32_16x16x32_bf16 v[110:113], v[144:147], v[194:197], v[110:113]
	v_mfma_f32_16x16x32_bf16 v[106:109], v[156:159], v[194:197], v[106:109]
	v_mfma_f32_16x16x32_bf16 v[94:97], v[144:147], v[222:225], v[94:97]
	v_mfma_f32_16x16x32_bf16 v[90:93], v[156:159], v[222:225], v[90:93]
	v_mfma_f32_16x16x32_bf16 v[78:81], v[144:147], v[234:237], v[78:81]
	v_mfma_f32_16x16x32_bf16 v[74:77], v[156:159], v[234:237], v[74:77]
	v_mfma_f32_16x16x32_bf16 v[118:121], v[160:163], v[182:185], v[118:121]
	v_mfma_f32_16x16x32_bf16 v[114:117], v[168:171], v[182:185], v[114:117]
	v_mfma_f32_16x16x32_bf16 v[102:105], v[160:163], v[190:193], v[102:105]
	v_mfma_f32_16x16x32_bf16 v[98:101], v[168:171], v[190:193], v[98:101]
	v_mfma_f32_16x16x32_bf16 v[86:89], v[160:163], v[218:221], v[86:89]
	v_mfma_f32_16x16x32_bf16 v[82:85], v[168:171], v[218:221], v[82:85]
	v_mfma_f32_16x16x32_bf16 v[70:73], v[160:163], v[230:233], v[70:73]
	v_mfma_f32_16x16x32_bf16 v[66:69], v[168:171], v[230:233], v[66:69]
	v_mfma_f32_16x16x32_bf16 v[118:121], v[164:167], v[186:189], v[118:121]
	v_mfma_f32_16x16x32_bf16 v[114:117], v[172:175], v[186:189], v[114:117]
	v_mfma_f32_16x16x32_bf16 v[102:105], v[164:167], v[194:197], v[102:105]
	v_mfma_f32_16x16x32_bf16 v[98:101], v[172:175], v[194:197], v[98:101]
	v_mfma_f32_16x16x32_bf16 v[86:89], v[164:167], v[222:225], v[86:89]
	v_mfma_f32_16x16x32_bf16 v[82:85], v[172:175], v[222:225], v[82:85]
	v_mfma_f32_16x16x32_bf16 v[70:73], v[164:167], v[234:237], v[70:73]
	v_mfma_f32_16x16x32_bf16 v[66:69], v[172:175], v[234:237], v[66:69]
	s_setprio 0
	s_barrier
	s_mov_b32 m0, s35
	v_lshl_add_u64 v[176:177], s[84:85], 0, v[0:1]
	v_lshl_add_u64 v[198:199], s[84:85], 0, v[134:135]
	s_add_u32 s84, s84, s10
	ds_read_b128 v[182:185], v151 offset:16384
	ds_read_b128 v[186:189], v151 offset:17408
	ds_read_b128 v[190:193], v151 offset:18432
	ds_read_b128 v[194:197], v151 offset:19456
	ds_read_b128 v[218:221], v151 offset:20480
	ds_read_b128 v[222:225], v151 offset:21504
	ds_read_b128 v[230:233], v151 offset:22528
	ds_read_b128 v[234:237], v151 offset:23552
	global_load_lds_dwordx4 v[176:177], off
	s_mov_b32 m0, s37
	s_addc_u32 s85, s85, s11
	global_load_lds_dwordx4 v[198:199], off
	v_lshl_add_u64 v[238:239], s[84:85], 0, v[0:1]
	s_mov_b32 m0, s46
	v_lshl_add_u64 v[240:241], s[84:85], 0, v[134:135]
	global_load_lds_dwordx4 v[238:239], off
	s_mov_b32 m0, s47
	v_lshl_add_u64 v[242:243], s[28:29], 0, v[130:131]
	global_load_lds_dwordx4 v[240:241], off
	s_mov_b32 m0, s50
	v_lshl_add_u64 v[244:245], s[28:29], 0, v[132:133]
	global_load_lds_dwordx4 v[242:243], off
	s_mov_b32 m0, s51
	s_nop 0
	global_load_lds_dwordx4 v[244:245], off
	s_waitcnt vmcnt(8)
	s_waitcnt lgkmcnt(0)
	s_barrier
	s_setprio 1
	s_waitcnt lgkmcnt(0)
	v_mfma_f32_16x16x32_bf16 v[62:65], v[140:143], v[182:185], v[62:65]
	v_mfma_f32_16x16x32_bf16 v[58:61], v[152:155], v[182:185], v[58:61]
	v_mfma_f32_16x16x32_bf16 v[46:49], v[140:143], v[190:193], v[46:49]
	v_mfma_f32_16x16x32_bf16 v[42:45], v[152:155], v[190:193], v[42:45]
	v_mfma_f32_16x16x32_bf16 v[30:33], v[140:143], v[218:221], v[30:33]
	v_mfma_f32_16x16x32_bf16 v[26:29], v[152:155], v[218:221], v[26:29]
	v_mfma_f32_16x16x32_bf16 v[14:17], v[140:143], v[230:233], v[14:17]
	v_mfma_f32_16x16x32_bf16 v[10:13], v[152:155], v[230:233], v[10:13]
	v_mfma_f32_16x16x32_bf16 v[62:65], v[144:147], v[186:189], v[62:65]
	v_mfma_f32_16x16x32_bf16 v[58:61], v[156:159], v[186:189], v[58:61]
	v_mfma_f32_16x16x32_bf16 v[46:49], v[144:147], v[194:197], v[46:49]
	v_mfma_f32_16x16x32_bf16 v[42:45], v[156:159], v[194:197], v[42:45]
	v_mfma_f32_16x16x32_bf16 v[30:33], v[144:147], v[222:225], v[30:33]
	v_mfma_f32_16x16x32_bf16 v[26:29], v[156:159], v[222:225], v[26:29]
	v_mfma_f32_16x16x32_bf16 v[14:17], v[144:147], v[234:237], v[14:17]
	v_mfma_f32_16x16x32_bf16 v[10:13], v[156:159], v[234:237], v[10:13]
	v_mfma_f32_16x16x32_bf16 v[54:57], v[160:163], v[182:185], v[54:57]
	v_mfma_f32_16x16x32_bf16 v[50:53], v[168:171], v[182:185], v[50:53]
	v_mfma_f32_16x16x32_bf16 v[38:41], v[160:163], v[190:193], v[38:41]
	v_mfma_f32_16x16x32_bf16 v[34:37], v[168:171], v[190:193], v[34:37]
	v_mfma_f32_16x16x32_bf16 v[22:25], v[160:163], v[218:221], v[22:25]
	v_mfma_f32_16x16x32_bf16 v[18:21], v[168:171], v[218:221], v[18:21]
	v_mfma_f32_16x16x32_bf16 v[6:9], v[160:163], v[230:233], v[6:9]
	v_mfma_f32_16x16x32_bf16 v[2:5], v[168:171], v[230:233], v[2:5]
	v_mfma_f32_16x16x32_bf16 v[54:57], v[164:167], v[186:189], v[54:57]
	v_mfma_f32_16x16x32_bf16 v[50:53], v[172:175], v[186:189], v[50:53]
	v_mfma_f32_16x16x32_bf16 v[38:41], v[164:167], v[194:197], v[38:41]
	v_mfma_f32_16x16x32_bf16 v[34:37], v[172:175], v[194:197], v[34:37]
	v_mfma_f32_16x16x32_bf16 v[22:25], v[164:167], v[222:225], v[22:25]
	v_mfma_f32_16x16x32_bf16 v[18:21], v[172:175], v[222:225], v[18:21]
	v_mfma_f32_16x16x32_bf16 v[6:9], v[164:167], v[234:237], v[6:9]
	v_mfma_f32_16x16x32_bf16 v[2:5], v[172:175], v[234:237], v[2:5]
	s_setprio 0
	s_barrier
	v_add_u32_e32 v156, s58, v150
	v_add_u32_e32 v172, s63, v150
	ds_read_b128 v[140:143], v156
	ds_read_b128 v[144:147], v156 offset:1024
	ds_read_b128 v[152:155], v156 offset:2048
	ds_read_b128 v[156:159], v156 offset:3072
	ds_read_b128 v[160:163], v172
	ds_read_b128 v[164:167], v172 offset:1024
	ds_read_b128 v[168:171], v172 offset:2048
	ds_read_b128 v[172:175], v172 offset:3072
	s_add_u32 s28, s28, s8
	s_addc_u32 s29, s29, s9
	s_mov_b32 m0, s52
	v_lshl_add_u64 v[246:247], s[28:29], 0, v[130:131]
	ds_read_b128 v[182:185], v151 offset:32768
	ds_read_b128 v[186:189], v151 offset:33792
	ds_read_b128 v[190:193], v151 offset:34816
	ds_read_b128 v[194:197], v151 offset:35840
	ds_read_b128 v[218:221], v151 offset:36864
	ds_read_b128 v[222:225], v151 offset:37888
	ds_read_b128 v[230:233], v151 offset:38912
	ds_read_b128 v[234:237], v151 offset:39936
	global_load_lds_dwordx4 v[246:247], off
	v_lshl_add_u64 v[246:247], s[28:29], 0, v[132:133]
	s_mov_b32 m0, s53
	s_nop 0
	global_load_lds_dwordx4 v[246:247], off
	s_waitcnt vmcnt(8)
	s_waitcnt lgkmcnt(0)
	s_barrier
	s_setprio 1
	s_waitcnt lgkmcnt(0)
	v_mfma_f32_16x16x32_bf16 v[122:125], v[140:143], v[182:185], v[122:125]
	v_mfma_f32_16x16x32_bf16 v[126:129], v[152:155], v[182:185], v[126:129]
	v_mfma_f32_16x16x32_bf16 v[110:113], v[140:143], v[190:193], v[110:113]
	v_mfma_f32_16x16x32_bf16 v[106:109], v[152:155], v[190:193], v[106:109]
	v_mfma_f32_16x16x32_bf16 v[94:97], v[140:143], v[218:221], v[94:97]
	v_mfma_f32_16x16x32_bf16 v[90:93], v[152:155], v[218:221], v[90:93]
	v_mfma_f32_16x16x32_bf16 v[78:81], v[140:143], v[230:233], v[78:81]
	v_mfma_f32_16x16x32_bf16 v[74:77], v[152:155], v[230:233], v[74:77]
	v_mfma_f32_16x16x32_bf16 v[122:125], v[144:147], v[186:189], v[122:125]
	v_mfma_f32_16x16x32_bf16 v[126:129], v[156:159], v[186:189], v[126:129]
	v_mfma_f32_16x16x32_bf16 v[110:113], v[144:147], v[194:197], v[110:113]
	v_mfma_f32_16x16x32_bf16 v[106:109], v[156:159], v[194:197], v[106:109]
	v_mfma_f32_16x16x32_bf16 v[94:97], v[144:147], v[222:225], v[94:97]
	v_mfma_f32_16x16x32_bf16 v[90:93], v[156:159], v[222:225], v[90:93]
	v_mfma_f32_16x16x32_bf16 v[78:81], v[144:147], v[234:237], v[78:81]
	v_mfma_f32_16x16x32_bf16 v[74:77], v[156:159], v[234:237], v[74:77]
	v_mfma_f32_16x16x32_bf16 v[118:121], v[160:163], v[182:185], v[118:121]
	v_mfma_f32_16x16x32_bf16 v[114:117], v[168:171], v[182:185], v[114:117]
	v_mfma_f32_16x16x32_bf16 v[102:105], v[160:163], v[190:193], v[102:105]
	v_mfma_f32_16x16x32_bf16 v[98:101], v[168:171], v[190:193], v[98:101]
	v_mfma_f32_16x16x32_bf16 v[86:89], v[160:163], v[218:221], v[86:89]
	v_mfma_f32_16x16x32_bf16 v[82:85], v[168:171], v[218:221], v[82:85]
	v_mfma_f32_16x16x32_bf16 v[70:73], v[160:163], v[230:233], v[70:73]
	v_mfma_f32_16x16x32_bf16 v[66:69], v[168:171], v[230:233], v[66:69]
	v_mfma_f32_16x16x32_bf16 v[118:121], v[164:167], v[186:189], v[118:121]
	v_mfma_f32_16x16x32_bf16 v[114:117], v[172:175], v[186:189], v[114:117]
	v_mfma_f32_16x16x32_bf16 v[102:105], v[164:167], v[194:197], v[102:105]
	v_mfma_f32_16x16x32_bf16 v[98:101], v[172:175], v[194:197], v[98:101]
	v_mfma_f32_16x16x32_bf16 v[86:89], v[164:167], v[222:225], v[86:89]
	v_mfma_f32_16x16x32_bf16 v[82:85], v[172:175], v[222:225], v[82:85]
	v_mfma_f32_16x16x32_bf16 v[70:73], v[164:167], v[234:237], v[70:73]
	v_mfma_f32_16x16x32_bf16 v[66:69], v[172:175], v[234:237], v[66:69]
	s_setprio 0
	s_barrier
	s_mov_b32 m0, s59
	v_lshl_add_u64 v[176:177], v[176:177], 0, s[48:49]
	ds_read_b128 v[182:185], v151 offset:49152
	ds_read_b128 v[186:189], v151 offset:50176
	ds_read_b128 v[190:193], v151 offset:51200
	ds_read_b128 v[194:197], v151 offset:52224
	ds_read_b128 v[218:221], v151 offset:53248
	ds_read_b128 v[222:225], v151 offset:54272
	ds_read_b128 v[230:233], v151 offset:55296
	ds_read_b128 v[234:237], v151 offset:56320
	global_load_lds_dwordx4 v[176:177], off
	v_lshl_add_u64 v[176:177], v[198:199], 0, s[48:49]
	s_mov_b32 m0, s60
	s_nop 0
	global_load_lds_dwordx4 v[176:177], off
	v_lshl_add_u64 v[176:177], v[238:239], 0, s[48:49]
	s_mov_b32 m0, s64
	s_nop 0
	global_load_lds_dwordx4 v[176:177], off
	v_lshl_add_u64 v[176:177], v[240:241], 0, s[48:49]
	s_mov_b32 m0, s65
	s_nop 0
	global_load_lds_dwordx4 v[176:177], off
	v_lshl_add_u64 v[176:177], v[242:243], 0, s[48:49]
	s_mov_b32 m0, s61
	s_nop 0
	global_load_lds_dwordx4 v[176:177], off
	v_lshl_add_u64 v[176:177], v[244:245], 0, s[48:49]
	s_mov_b32 m0, s62
	s_nop 0
	global_load_lds_dwordx4 v[176:177], off
	s_waitcnt vmcnt(8)
	s_waitcnt lgkmcnt(0)
	s_barrier
	s_setprio 1
	s_waitcnt lgkmcnt(0)
	v_mfma_f32_16x16x32_bf16 v[62:65], v[140:143], v[182:185], v[62:65]
	v_mfma_f32_16x16x32_bf16 v[58:61], v[152:155], v[182:185], v[58:61]
	v_mfma_f32_16x16x32_bf16 v[46:49], v[140:143], v[190:193], v[46:49]
	v_mfma_f32_16x16x32_bf16 v[42:45], v[152:155], v[190:193], v[42:45]
	v_mfma_f32_16x16x32_bf16 v[30:33], v[140:143], v[218:221], v[30:33]
	v_mfma_f32_16x16x32_bf16 v[26:29], v[152:155], v[218:221], v[26:29]
	v_mfma_f32_16x16x32_bf16 v[14:17], v[140:143], v[230:233], v[14:17]
	v_mfma_f32_16x16x32_bf16 v[10:13], v[152:155], v[230:233], v[10:13]
	v_mfma_f32_16x16x32_bf16 v[62:65], v[144:147], v[186:189], v[62:65]
	v_mfma_f32_16x16x32_bf16 v[58:61], v[156:159], v[186:189], v[58:61]
	v_mfma_f32_16x16x32_bf16 v[46:49], v[144:147], v[194:197], v[46:49]
	v_mfma_f32_16x16x32_bf16 v[42:45], v[156:159], v[194:197], v[42:45]
	v_mfma_f32_16x16x32_bf16 v[30:33], v[144:147], v[222:225], v[30:33]
	v_mfma_f32_16x16x32_bf16 v[26:29], v[156:159], v[222:225], v[26:29]
	v_mfma_f32_16x16x32_bf16 v[14:17], v[144:147], v[234:237], v[14:17]
	v_mfma_f32_16x16x32_bf16 v[10:13], v[156:159], v[234:237], v[10:13]
	v_mfma_f32_16x16x32_bf16 v[54:57], v[160:163], v[182:185], v[54:57]
	v_mfma_f32_16x16x32_bf16 v[50:53], v[168:171], v[182:185], v[50:53]
	v_mfma_f32_16x16x32_bf16 v[38:41], v[160:163], v[190:193], v[38:41]
	v_mfma_f32_16x16x32_bf16 v[34:37], v[168:171], v[190:193], v[34:37]
	v_mfma_f32_16x16x32_bf16 v[22:25], v[160:163], v[218:221], v[22:25]
	v_mfma_f32_16x16x32_bf16 v[18:21], v[168:171], v[218:221], v[18:21]
	v_mfma_f32_16x16x32_bf16 v[6:9], v[160:163], v[230:233], v[6:9]
	v_mfma_f32_16x16x32_bf16 v[2:5], v[168:171], v[230:233], v[2:5]
	v_mfma_f32_16x16x32_bf16 v[54:57], v[164:167], v[186:189], v[54:57]
	v_mfma_f32_16x16x32_bf16 v[50:53], v[172:175], v[186:189], v[50:53]
	v_mfma_f32_16x16x32_bf16 v[38:41], v[164:167], v[194:197], v[38:41]
	v_mfma_f32_16x16x32_bf16 v[34:37], v[172:175], v[194:197], v[34:37]
	v_mfma_f32_16x16x32_bf16 v[22:25], v[164:167], v[222:225], v[22:25]
	v_mfma_f32_16x16x32_bf16 v[18:21], v[172:175], v[222:225], v[18:21]
	v_mfma_f32_16x16x32_bf16 v[6:9], v[164:167], v[234:237], v[6:9]
	v_mfma_f32_16x16x32_bf16 v[2:5], v[172:175], v[234:237], v[2:5]
	s_setprio 0
	s_barrier
	s_add_u32 s81, s81, 0x100
	s_addc_u32 s82, s82, 0
	s_add_u32 s4, s4, 0x100
	s_addc_u32 s5, s5, 0
	s_cmp_ge_i32 s83, s55
	s_mov_b32 s28, s83
	s_cbranch_scc0 .LBB0_763

.LBB0_1024:
	v_add_u32_e32 v144, s66, v148
	ds_read_b128 v[140:143], v144
	ds_read_b128 v[150:153], v144 offset:1024
	ds_read_b128 v[154:157], v144 offset:2048
	ds_read_b128 v[158:161], v144 offset:3072
	v_add_u32_e32 v144, s69, v148
	ds_read_b128 v[162:165], v144
	ds_read_b128 v[166:169], v144 offset:1024
	ds_read_b128 v[170:173], v144 offset:2048
	ds_read_b128 v[174:177], v144 offset:3072
	s_add_i32 s52, s28, 2
	s_add_u32 s54, s26, 0x80
	s_addc_u32 s29, s27, 0
	s_cmp_eq_u32 s88, s28
	s_cselect_b32 s28, s0, s54
	s_cselect_b32 s29, s1, s29
	s_cselect_b32 s59, s25, s47
	s_cselect_b32 s58, s24, s46
	v_lshl_add_u64 v[144:145], s[26:27], 0, v[138:139]
	s_add_i32 m0, s72, 0xc000
	ds_read_b128 v[182:185], v149
	ds_read_b128 v[186:189], v149 offset:1024
	ds_read_b128 v[190:193], v149 offset:2048
	ds_read_b128 v[194:197], v149 offset:3072
	ds_read_b128 v[218:221], v149 offset:4096
	ds_read_b128 v[222:225], v149 offset:5120
	ds_read_b128 v[230:233], v149 offset:6144
	ds_read_b128 v[234:237], v149 offset:7168
	global_load_lds_dwordx4 v[144:145], off
	v_lshl_add_u64 v[144:145], s[26:27], 0, v[136:137]
	s_add_i32 m0, s72, 0xe000
	s_nop 0
	global_load_lds_dwordx4 v[144:145], off
	s_waitcnt vmcnt(8)
	s_waitcnt lgkmcnt(0)
	s_barrier
	s_setprio 1
	s_waitcnt lgkmcnt(0)
	v_mfma_f32_16x16x32_bf16 v[126:129], v[140:143], v[182:185], v[126:129]
	v_mfma_f32_16x16x32_bf16 v[122:125], v[154:157], v[182:185], v[122:125]
	v_mfma_f32_16x16x32_bf16 v[110:113], v[140:143], v[190:193], v[110:113]
	v_mfma_f32_16x16x32_bf16 v[106:109], v[154:157], v[190:193], v[106:109]
	v_mfma_f32_16x16x32_bf16 v[94:97], v[140:143], v[218:221], v[94:97]
	v_mfma_f32_16x16x32_bf16 v[90:93], v[154:157], v[218:221], v[90:93]
	v_mfma_f32_16x16x32_bf16 v[78:81], v[140:143], v[230:233], v[78:81]
	v_mfma_f32_16x16x32_bf16 v[74:77], v[154:157], v[230:233], v[74:77]
	v_mfma_f32_16x16x32_bf16 v[126:129], v[150:153], v[186:189], v[126:129]
	v_mfma_f32_16x16x32_bf16 v[122:125], v[158:161], v[186:189], v[122:125]
	v_mfma_f32_16x16x32_bf16 v[110:113], v[150:153], v[194:197], v[110:113]
	v_mfma_f32_16x16x32_bf16 v[106:109], v[158:161], v[194:197], v[106:109]
	v_mfma_f32_16x16x32_bf16 v[94:97], v[150:153], v[222:225], v[94:97]
	v_mfma_f32_16x16x32_bf16 v[90:93], v[158:161], v[222:225], v[90:93]
	v_mfma_f32_16x16x32_bf16 v[78:81], v[150:153], v[234:237], v[78:81]
	v_mfma_f32_16x16x32_bf16 v[74:77], v[158:161], v[234:237], v[74:77]
	v_mfma_f32_16x16x32_bf16 v[118:121], v[162:165], v[182:185], v[118:121]
	v_mfma_f32_16x16x32_bf16 v[114:117], v[170:173], v[182:185], v[114:117]
	v_mfma_f32_16x16x32_bf16 v[102:105], v[162:165], v[190:193], v[102:105]
	v_mfma_f32_16x16x32_bf16 v[98:101], v[170:173], v[190:193], v[98:101]
	v_mfma_f32_16x16x32_bf16 v[86:89], v[162:165], v[218:221], v[86:89]
	v_mfma_f32_16x16x32_bf16 v[82:85], v[170:173], v[218:221], v[82:85]
	v_mfma_f32_16x16x32_bf16 v[70:73], v[162:165], v[230:233], v[70:73]
	v_mfma_f32_16x16x32_bf16 v[66:69], v[170:173], v[230:233], v[66:69]
	v_mfma_f32_16x16x32_bf16 v[118:121], v[166:169], v[186:189], v[118:121]
	v_mfma_f32_16x16x32_bf16 v[114:117], v[174:177], v[186:189], v[114:117]
	v_mfma_f32_16x16x32_bf16 v[102:105], v[166:169], v[194:197], v[102:105]
	v_mfma_f32_16x16x32_bf16 v[98:101], v[174:177], v[194:197], v[98:101]
	v_mfma_f32_16x16x32_bf16 v[86:89], v[166:169], v[222:225], v[86:89]
	v_mfma_f32_16x16x32_bf16 v[82:85], v[174:177], v[222:225], v[82:85]
	v_mfma_f32_16x16x32_bf16 v[70:73], v[166:169], v[234:237], v[70:73]
	v_mfma_f32_16x16x32_bf16 v[66:69], v[174:177], v[234:237], v[66:69]
	s_setprio 0
	s_barrier
	s_mov_b32 m0, s67
	v_lshl_add_u64 v[144:145], s[58:59], 0, v[0:1]
	v_lshl_add_u64 v[198:199], s[58:59], 0, v[130:131]
	s_add_u32 s58, s58, s8
	ds_read_b128 v[182:185], v149 offset:16384
	ds_read_b128 v[186:189], v149 offset:17408
	ds_read_b128 v[190:193], v149 offset:18432
	ds_read_b128 v[194:197], v149 offset:19456
	ds_read_b128 v[218:221], v149 offset:20480
	ds_read_b128 v[222:225], v149 offset:21504
	ds_read_b128 v[230:233], v149 offset:22528
	ds_read_b128 v[234:237], v149 offset:23552
	global_load_lds_dwordx4 v[144:145], off
	s_mov_b32 m0, s68
	s_addc_u32 s59, s59, s9
	global_load_lds_dwordx4 v[198:199], off
	v_lshl_add_u64 v[238:239], s[58:59], 0, v[0:1]
	s_mov_b32 m0, s70
	v_lshl_add_u64 v[240:241], s[58:59], 0, v[130:131]
	global_load_lds_dwordx4 v[238:239], off
	s_mov_b32 m0, s71
	v_lshl_add_u64 v[242:243], s[28:29], 0, v[134:135]
	global_load_lds_dwordx4 v[240:241], off
	s_mov_b32 m0, s72
	v_lshl_add_u64 v[244:245], s[28:29], 0, v[132:133]
	global_load_lds_dwordx4 v[242:243], off
	s_mov_b32 m0, s73
	s_nop 0
	global_load_lds_dwordx4 v[244:245], off
	s_waitcnt vmcnt(8)
	s_waitcnt lgkmcnt(0)
	s_barrier
	s_setprio 1
	s_waitcnt lgkmcnt(0)
	v_mfma_f32_16x16x32_bf16 v[62:65], v[140:143], v[182:185], v[62:65]
	v_mfma_f32_16x16x32_bf16 v[58:61], v[154:157], v[182:185], v[58:61]
	v_mfma_f32_16x16x32_bf16 v[46:49], v[140:143], v[190:193], v[46:49]
	v_mfma_f32_16x16x32_bf16 v[42:45], v[154:157], v[190:193], v[42:45]
	v_mfma_f32_16x16x32_bf16 v[30:33], v[140:143], v[218:221], v[30:33]
	v_mfma_f32_16x16x32_bf16 v[26:29], v[154:157], v[218:221], v[26:29]
	v_mfma_f32_16x16x32_bf16 v[14:17], v[140:143], v[230:233], v[14:17]
	v_mfma_f32_16x16x32_bf16 v[10:13], v[154:157], v[230:233], v[10:13]
	v_mfma_f32_16x16x32_bf16 v[62:65], v[150:153], v[186:189], v[62:65]
	v_mfma_f32_16x16x32_bf16 v[58:61], v[158:161], v[186:189], v[58:61]
	v_mfma_f32_16x16x32_bf16 v[46:49], v[150:153], v[194:197], v[46:49]
	v_mfma_f32_16x16x32_bf16 v[42:45], v[158:161], v[194:197], v[42:45]
	v_mfma_f32_16x16x32_bf16 v[30:33], v[150:153], v[222:225], v[30:33]
	v_mfma_f32_16x16x32_bf16 v[26:29], v[158:161], v[222:225], v[26:29]
	v_mfma_f32_16x16x32_bf16 v[14:17], v[150:153], v[234:237], v[14:17]
	v_mfma_f32_16x16x32_bf16 v[10:13], v[158:161], v[234:237], v[10:13]
	v_mfma_f32_16x16x32_bf16 v[54:57], v[162:165], v[182:185], v[54:57]
	v_mfma_f32_16x16x32_bf16 v[50:53], v[170:173], v[182:185], v[50:53]
	v_mfma_f32_16x16x32_bf16 v[38:41], v[162:165], v[190:193], v[38:41]
	v_mfma_f32_16x16x32_bf16 v[34:37], v[170:173], v[190:193], v[34:37]
	v_mfma_f32_16x16x32_bf16 v[22:25], v[162:165], v[218:221], v[22:25]
	v_mfma_f32_16x16x32_bf16 v[18:21], v[170:173], v[218:221], v[18:21]
	v_mfma_f32_16x16x32_bf16 v[6:9], v[162:165], v[230:233], v[6:9]
	v_mfma_f32_16x16x32_bf16 v[2:5], v[170:173], v[230:233], v[2:5]
	v_mfma_f32_16x16x32_bf16 v[54:57], v[166:169], v[186:189], v[54:57]
	v_mfma_f32_16x16x32_bf16 v[50:53], v[174:177], v[186:189], v[50:53]
	v_mfma_f32_16x16x32_bf16 v[38:41], v[166:169], v[194:197], v[38:41]
	v_mfma_f32_16x16x32_bf16 v[34:37], v[174:177], v[194:197], v[34:37]
	v_mfma_f32_16x16x32_bf16 v[22:25], v[166:169], v[222:225], v[22:25]
	v_mfma_f32_16x16x32_bf16 v[18:21], v[174:177], v[222:225], v[18:21]
	v_mfma_f32_16x16x32_bf16 v[6:9], v[166:169], v[234:237], v[6:9]
	v_mfma_f32_16x16x32_bf16 v[2:5], v[174:177], v[234:237], v[2:5]
	s_setprio 0
	s_barrier
	v_add_u32_e32 v158, s78, v148
	v_add_u32_e32 v174, s83, v148
	ds_read_b128 v[140:143], v158
	ds_read_b128 v[150:153], v158 offset:1024
	ds_read_b128 v[154:157], v158 offset:2048
	ds_read_b128 v[158:161], v158 offset:3072
	ds_read_b128 v[162:165], v174
	ds_read_b128 v[166:169], v174 offset:1024
	ds_read_b128 v[170:173], v174 offset:2048
	ds_read_b128 v[174:177], v174 offset:3072
	s_add_u32 s28, s28, s6
	s_addc_u32 s29, s29, s7
	s_mov_b32 m0, s74
	v_lshl_add_u64 v[246:247], s[28:29], 0, v[134:135]
	ds_read_b128 v[182:185], v149 offset:32768
	ds_read_b128 v[186:189], v149 offset:33792
	ds_read_b128 v[190:193], v149 offset:34816
	ds_read_b128 v[194:197], v149 offset:35840
	ds_read_b128 v[218:221], v149 offset:36864
	ds_read_b128 v[222:225], v149 offset:37888
	ds_read_b128 v[230:233], v149 offset:38912
	ds_read_b128 v[234:237], v149 offset:39936
	global_load_lds_dwordx4 v[246:247], off
	v_lshl_add_u64 v[246:247], s[28:29], 0, v[132:133]
	s_mov_b32 m0, s75
	s_nop 0
	global_load_lds_dwordx4 v[246:247], off
	s_waitcnt vmcnt(8)
	s_waitcnt lgkmcnt(0)
	s_barrier
	s_setprio 1
	s_waitcnt lgkmcnt(0)
	v_mfma_f32_16x16x32_bf16 v[126:129], v[140:143], v[182:185], v[126:129]
	v_mfma_f32_16x16x32_bf16 v[122:125], v[154:157], v[182:185], v[122:125]
	v_mfma_f32_16x16x32_bf16 v[110:113], v[140:143], v[190:193], v[110:113]
	v_mfma_f32_16x16x32_bf16 v[106:109], v[154:157], v[190:193], v[106:109]
	v_mfma_f32_16x16x32_bf16 v[94:97], v[140:143], v[218:221], v[94:97]
	v_mfma_f32_16x16x32_bf16 v[90:93], v[154:157], v[218:221], v[90:93]
	v_mfma_f32_16x16x32_bf16 v[78:81], v[140:143], v[230:233], v[78:81]
	v_mfma_f32_16x16x32_bf16 v[74:77], v[154:157], v[230:233], v[74:77]
	v_mfma_f32_16x16x32_bf16 v[126:129], v[150:153], v[186:189], v[126:129]
	v_mfma_f32_16x16x32_bf16 v[122:125], v[158:161], v[186:189], v[122:125]
	v_mfma_f32_16x16x32_bf16 v[110:113], v[150:153], v[194:197], v[110:113]
	v_mfma_f32_16x16x32_bf16 v[106:109], v[158:161], v[194:197], v[106:109]
	v_mfma_f32_16x16x32_bf16 v[94:97], v[150:153], v[222:225], v[94:97]
	v_mfma_f32_16x16x32_bf16 v[90:93], v[158:161], v[222:225], v[90:93]
	v_mfma_f32_16x16x32_bf16 v[78:81], v[150:153], v[234:237], v[78:81]
	v_mfma_f32_16x16x32_bf16 v[74:77], v[158:161], v[234:237], v[74:77]
	v_mfma_f32_16x16x32_bf16 v[118:121], v[162:165], v[182:185], v[118:121]
	v_mfma_f32_16x16x32_bf16 v[114:117], v[170:173], v[182:185], v[114:117]
	v_mfma_f32_16x16x32_bf16 v[102:105], v[162:165], v[190:193], v[102:105]
	v_mfma_f32_16x16x32_bf16 v[98:101], v[170:173], v[190:193], v[98:101]
	v_mfma_f32_16x16x32_bf16 v[86:89], v[162:165], v[218:221], v[86:89]
	v_mfma_f32_16x16x32_bf16 v[82:85], v[170:173], v[218:221], v[82:85]
	v_mfma_f32_16x16x32_bf16 v[70:73], v[162:165], v[230:233], v[70:73]
	v_mfma_f32_16x16x32_bf16 v[66:69], v[170:173], v[230:233], v[66:69]
	v_mfma_f32_16x16x32_bf16 v[118:121], v[166:169], v[186:189], v[118:121]
	v_mfma_f32_16x16x32_bf16 v[114:117], v[174:177], v[186:189], v[114:117]
	v_mfma_f32_16x16x32_bf16 v[102:105], v[166:169], v[194:197], v[102:105]
	v_mfma_f32_16x16x32_bf16 v[98:101], v[174:177], v[194:197], v[98:101]
	v_mfma_f32_16x16x32_bf16 v[86:89], v[166:169], v[222:225], v[86:89]
	v_mfma_f32_16x16x32_bf16 v[82:85], v[174:177], v[222:225], v[82:85]
	v_mfma_f32_16x16x32_bf16 v[70:73], v[166:169], v[234:237], v[70:73]
	v_mfma_f32_16x16x32_bf16 v[66:69], v[174:177], v[234:237], v[66:69]
	s_setprio 0
	s_barrier
	s_mov_b32 m0, s79
	v_lshl_add_u64 v[144:145], v[144:145], 0, s[48:49]
	ds_read_b128 v[182:185], v149 offset:49152
	ds_read_b128 v[186:189], v149 offset:50176
	ds_read_b128 v[190:193], v149 offset:51200
	ds_read_b128 v[194:197], v149 offset:52224
	ds_read_b128 v[218:221], v149 offset:53248
	ds_read_b128 v[222:225], v149 offset:54272
	ds_read_b128 v[230:233], v149 offset:55296
	ds_read_b128 v[234:237], v149 offset:56320
	global_load_lds_dwordx4 v[144:145], off
	v_lshl_add_u64 v[144:145], v[198:199], 0, s[48:49]
	s_mov_b32 m0, s80
	s_nop 0
	global_load_lds_dwordx4 v[144:145], off
	v_lshl_add_u64 v[144:145], v[238:239], 0, s[48:49]
	s_mov_b32 m0, s84
	s_nop 0
	global_load_lds_dwordx4 v[144:145], off
	v_lshl_add_u64 v[144:145], v[240:241], 0, s[48:49]
	s_mov_b32 m0, s85
	s_nop 0
	global_load_lds_dwordx4 v[144:145], off
	v_lshl_add_u64 v[144:145], v[242:243], 0, s[48:49]
	s_mov_b32 m0, s81
	s_nop 0
	global_load_lds_dwordx4 v[144:145], off
	v_lshl_add_u64 v[144:145], v[244:245], 0, s[48:49]
	s_mov_b32 m0, s82
	s_nop 0
	global_load_lds_dwordx4 v[144:145], off
	s_waitcnt vmcnt(8)
	s_waitcnt lgkmcnt(0)
	s_barrier
	s_setprio 1
	s_waitcnt lgkmcnt(0)
	v_mfma_f32_16x16x32_bf16 v[62:65], v[140:143], v[182:185], v[62:65]
	v_mfma_f32_16x16x32_bf16 v[58:61], v[154:157], v[182:185], v[58:61]
	v_mfma_f32_16x16x32_bf16 v[46:49], v[140:143], v[190:193], v[46:49]
	v_mfma_f32_16x16x32_bf16 v[42:45], v[154:157], v[190:193], v[42:45]
	v_mfma_f32_16x16x32_bf16 v[30:33], v[140:143], v[218:221], v[30:33]
	v_mfma_f32_16x16x32_bf16 v[26:29], v[154:157], v[218:221], v[26:29]
	v_mfma_f32_16x16x32_bf16 v[14:17], v[140:143], v[230:233], v[14:17]
	v_mfma_f32_16x16x32_bf16 v[10:13], v[154:157], v[230:233], v[10:13]
	v_mfma_f32_16x16x32_bf16 v[62:65], v[150:153], v[186:189], v[62:65]
	v_mfma_f32_16x16x32_bf16 v[58:61], v[158:161], v[186:189], v[58:61]
	v_mfma_f32_16x16x32_bf16 v[46:49], v[150:153], v[194:197], v[46:49]
	v_mfma_f32_16x16x32_bf16 v[42:45], v[158:161], v[194:197], v[42:45]
	v_mfma_f32_16x16x32_bf16 v[30:33], v[150:153], v[222:225], v[30:33]
	v_mfma_f32_16x16x32_bf16 v[26:29], v[158:161], v[222:225], v[26:29]
	v_mfma_f32_16x16x32_bf16 v[14:17], v[150:153], v[234:237], v[14:17]
	v_mfma_f32_16x16x32_bf16 v[10:13], v[158:161], v[234:237], v[10:13]
	v_mfma_f32_16x16x32_bf16 v[54:57], v[162:165], v[182:185], v[54:57]
	v_mfma_f32_16x16x32_bf16 v[50:53], v[170:173], v[182:185], v[50:53]
	v_mfma_f32_16x16x32_bf16 v[38:41], v[162:165], v[190:193], v[38:41]
	v_mfma_f32_16x16x32_bf16 v[34:37], v[170:173], v[190:193], v[34:37]
	v_mfma_f32_16x16x32_bf16 v[22:25], v[162:165], v[218:221], v[22:25]
	v_mfma_f32_16x16x32_bf16 v[18:21], v[170:173], v[218:221], v[18:21]
	v_mfma_f32_16x16x32_bf16 v[6:9], v[162:165], v[230:233], v[6:9]
	v_mfma_f32_16x16x32_bf16 v[2:5], v[170:173], v[230:233], v[2:5]
	v_mfma_f32_16x16x32_bf16 v[54:57], v[166:169], v[186:189], v[54:57]
	v_mfma_f32_16x16x32_bf16 v[50:53], v[174:177], v[186:189], v[50:53]
	v_mfma_f32_16x16x32_bf16 v[38:41], v[166:169], v[194:197], v[38:41]
	v_mfma_f32_16x16x32_bf16 v[34:37], v[174:177], v[194:197], v[34:37]
	v_mfma_f32_16x16x32_bf16 v[22:25], v[166:169], v[222:225], v[22:25]
	v_mfma_f32_16x16x32_bf16 v[18:21], v[174:177], v[222:225], v[18:21]
	v_mfma_f32_16x16x32_bf16 v[6:9], v[166:169], v[234:237], v[6:9]
	v_mfma_f32_16x16x32_bf16 v[2:5], v[174:177], v[234:237], v[2:5]
	s_setprio 0
	s_barrier
	s_add_u32 s46, s46, 0x100
	s_addc_u32 s47, s47, 0
	s_add_u32 s26, s26, 0x100
	s_addc_u32 s27, s27, 0
	s_cmp_ge_i32 s52, s77
	s_mov_b32 s28, s52
	s_cbranch_scc0 .LBB0_1024

.LBB0_1045:
	v_add_u32_e32 v144, s74, v148
	ds_read_b128 v[140:143], v144
	ds_read_b128 v[150:153], v144 offset:1024
	ds_read_b128 v[154:157], v144 offset:2048
	ds_read_b128 v[158:161], v144 offset:3072
	v_add_u32_e32 v144, s77, v148
	ds_read_b128 v[162:165], v144
	ds_read_b128 v[166:169], v144 offset:1024
	ds_read_b128 v[170:173], v144 offset:2048
	ds_read_b128 v[174:177], v144 offset:3072
	s_add_i32 s52, s28, 2
	s_add_u32 s54, s26, 0x80
	s_addc_u32 s29, s27, 0
	s_cmp_eq_u32 s85, s28
	s_cselect_b32 s28, s0, s54
	s_cselect_b32 s29, s1, s29
	s_cselect_b32 s59, s25, s47
	s_cselect_b32 s58, s24, s46
	v_lshl_add_u64 v[144:145], s[26:27], 0, v[138:139]
	s_add_i32 m0, s80, 0xc000
	ds_read_b128 v[182:185], v149
	ds_read_b128 v[186:189], v149 offset:1024
	ds_read_b128 v[190:193], v149 offset:2048
	ds_read_b128 v[194:197], v149 offset:3072
	ds_read_b128 v[218:221], v149 offset:4096
	ds_read_b128 v[222:225], v149 offset:5120
	ds_read_b128 v[230:233], v149 offset:6144
	ds_read_b128 v[234:237], v149 offset:7168
	global_load_lds_dwordx4 v[144:145], off
	v_lshl_add_u64 v[144:145], s[26:27], 0, v[136:137]
	s_add_i32 m0, s80, 0xe000
	s_nop 0
	global_load_lds_dwordx4 v[144:145], off
	s_waitcnt vmcnt(8)
	s_waitcnt lgkmcnt(0)
	s_barrier
	s_setprio 1
	s_waitcnt lgkmcnt(0)
	v_mfma_f32_16x16x32_bf16 v[126:129], v[140:143], v[182:185], v[126:129]
	v_mfma_f32_16x16x32_bf16 v[122:125], v[154:157], v[182:185], v[122:125]
	v_mfma_f32_16x16x32_bf16 v[110:113], v[140:143], v[190:193], v[110:113]
	v_mfma_f32_16x16x32_bf16 v[106:109], v[154:157], v[190:193], v[106:109]
	v_mfma_f32_16x16x32_bf16 v[94:97], v[140:143], v[218:221], v[94:97]
	v_mfma_f32_16x16x32_bf16 v[90:93], v[154:157], v[218:221], v[90:93]
	v_mfma_f32_16x16x32_bf16 v[78:81], v[140:143], v[230:233], v[78:81]
	v_mfma_f32_16x16x32_bf16 v[74:77], v[154:157], v[230:233], v[74:77]
	v_mfma_f32_16x16x32_bf16 v[126:129], v[150:153], v[186:189], v[126:129]
	v_mfma_f32_16x16x32_bf16 v[122:125], v[158:161], v[186:189], v[122:125]
	v_mfma_f32_16x16x32_bf16 v[110:113], v[150:153], v[194:197], v[110:113]
	v_mfma_f32_16x16x32_bf16 v[106:109], v[158:161], v[194:197], v[106:109]
	v_mfma_f32_16x16x32_bf16 v[94:97], v[150:153], v[222:225], v[94:97]
	v_mfma_f32_16x16x32_bf16 v[90:93], v[158:161], v[222:225], v[90:93]
	v_mfma_f32_16x16x32_bf16 v[78:81], v[150:153], v[234:237], v[78:81]
	v_mfma_f32_16x16x32_bf16 v[74:77], v[158:161], v[234:237], v[74:77]
	v_mfma_f32_16x16x32_bf16 v[118:121], v[162:165], v[182:185], v[118:121]
	v_mfma_f32_16x16x32_bf16 v[114:117], v[170:173], v[182:185], v[114:117]
	v_mfma_f32_16x16x32_bf16 v[102:105], v[162:165], v[190:193], v[102:105]
	v_mfma_f32_16x16x32_bf16 v[98:101], v[170:173], v[190:193], v[98:101]
	v_mfma_f32_16x16x32_bf16 v[86:89], v[162:165], v[218:221], v[86:89]
	v_mfma_f32_16x16x32_bf16 v[82:85], v[170:173], v[218:221], v[82:85]
	v_mfma_f32_16x16x32_bf16 v[70:73], v[162:165], v[230:233], v[70:73]
	v_mfma_f32_16x16x32_bf16 v[66:69], v[170:173], v[230:233], v[66:69]
	v_mfma_f32_16x16x32_bf16 v[118:121], v[166:169], v[186:189], v[118:121]
	v_mfma_f32_16x16x32_bf16 v[114:117], v[174:177], v[186:189], v[114:117]
	v_mfma_f32_16x16x32_bf16 v[102:105], v[166:169], v[194:197], v[102:105]
	v_mfma_f32_16x16x32_bf16 v[98:101], v[174:177], v[194:197], v[98:101]
	v_mfma_f32_16x16x32_bf16 v[86:89], v[166:169], v[222:225], v[86:89]
	v_mfma_f32_16x16x32_bf16 v[82:85], v[174:177], v[222:225], v[82:85]
	v_mfma_f32_16x16x32_bf16 v[70:73], v[166:169], v[234:237], v[70:73]
	v_mfma_f32_16x16x32_bf16 v[66:69], v[174:177], v[234:237], v[66:69]
	s_setprio 0
	s_barrier
	s_mov_b32 m0, s75
	v_lshl_add_u64 v[144:145], s[58:59], 0, v[0:1]
	v_lshl_add_u64 v[198:199], s[58:59], 0, v[130:131]
	s_add_u32 s58, s58, s8
	ds_read_b128 v[182:185], v149 offset:16384
	ds_read_b128 v[186:189], v149 offset:17408
	ds_read_b128 v[190:193], v149 offset:18432
	ds_read_b128 v[194:197], v149 offset:19456
	ds_read_b128 v[218:221], v149 offset:20480
	ds_read_b128 v[222:225], v149 offset:21504
	ds_read_b128 v[230:233], v149 offset:22528
	ds_read_b128 v[234:237], v149 offset:23552
	global_load_lds_dwordx4 v[144:145], off
	s_mov_b32 m0, s76
	s_addc_u32 s59, s59, s9
	global_load_lds_dwordx4 v[198:199], off
	v_lshl_add_u64 v[238:239], s[58:59], 0, v[0:1]
	s_mov_b32 m0, s78
	v_lshl_add_u64 v[240:241], s[58:59], 0, v[130:131]
	global_load_lds_dwordx4 v[238:239], off
	s_mov_b32 m0, s79
	v_lshl_add_u64 v[242:243], s[28:29], 0, v[134:135]
	global_load_lds_dwordx4 v[240:241], off
	s_mov_b32 m0, s80
	v_lshl_add_u64 v[244:245], s[28:29], 0, v[132:133]
	global_load_lds_dwordx4 v[242:243], off
	s_mov_b32 m0, s81
	s_nop 0
	global_load_lds_dwordx4 v[244:245], off
	s_waitcnt vmcnt(8)
	s_waitcnt lgkmcnt(0)
	s_barrier
	s_setprio 1
	s_waitcnt lgkmcnt(0)
	v_mfma_f32_16x16x32_bf16 v[62:65], v[140:143], v[182:185], v[62:65]
	v_mfma_f32_16x16x32_bf16 v[58:61], v[154:157], v[182:185], v[58:61]
	v_mfma_f32_16x16x32_bf16 v[46:49], v[140:143], v[190:193], v[46:49]
	v_mfma_f32_16x16x32_bf16 v[42:45], v[154:157], v[190:193], v[42:45]
	v_mfma_f32_16x16x32_bf16 v[30:33], v[140:143], v[218:221], v[30:33]
	v_mfma_f32_16x16x32_bf16 v[26:29], v[154:157], v[218:221], v[26:29]
	v_mfma_f32_16x16x32_bf16 v[14:17], v[140:143], v[230:233], v[14:17]
	v_mfma_f32_16x16x32_bf16 v[10:13], v[154:157], v[230:233], v[10:13]
	v_mfma_f32_16x16x32_bf16 v[62:65], v[150:153], v[186:189], v[62:65]
	v_mfma_f32_16x16x32_bf16 v[58:61], v[158:161], v[186:189], v[58:61]
	v_mfma_f32_16x16x32_bf16 v[46:49], v[150:153], v[194:197], v[46:49]
	v_mfma_f32_16x16x32_bf16 v[42:45], v[158:161], v[194:197], v[42:45]
	v_mfma_f32_16x16x32_bf16 v[30:33], v[150:153], v[222:225], v[30:33]
	v_mfma_f32_16x16x32_bf16 v[26:29], v[158:161], v[222:225], v[26:29]
	v_mfma_f32_16x16x32_bf16 v[14:17], v[150:153], v[234:237], v[14:17]
	v_mfma_f32_16x16x32_bf16 v[10:13], v[158:161], v[234:237], v[10:13]
	v_mfma_f32_16x16x32_bf16 v[54:57], v[162:165], v[182:185], v[54:57]
	v_mfma_f32_16x16x32_bf16 v[50:53], v[170:173], v[182:185], v[50:53]
	v_mfma_f32_16x16x32_bf16 v[38:41], v[162:165], v[190:193], v[38:41]
	v_mfma_f32_16x16x32_bf16 v[34:37], v[170:173], v[190:193], v[34:37]
	v_mfma_f32_16x16x32_bf16 v[22:25], v[162:165], v[218:221], v[22:25]
	v_mfma_f32_16x16x32_bf16 v[18:21], v[170:173], v[218:221], v[18:21]
	v_mfma_f32_16x16x32_bf16 v[6:9], v[162:165], v[230:233], v[6:9]
	v_mfma_f32_16x16x32_bf16 v[2:5], v[170:173], v[230:233], v[2:5]
	v_mfma_f32_16x16x32_bf16 v[54:57], v[166:169], v[186:189], v[54:57]
	v_mfma_f32_16x16x32_bf16 v[50:53], v[174:177], v[186:189], v[50:53]
	v_mfma_f32_16x16x32_bf16 v[38:41], v[166:169], v[194:197], v[38:41]
	v_mfma_f32_16x16x32_bf16 v[34:37], v[174:177], v[194:197], v[34:37]
	v_mfma_f32_16x16x32_bf16 v[22:25], v[166:169], v[222:225], v[22:25]
	v_mfma_f32_16x16x32_bf16 v[18:21], v[174:177], v[222:225], v[18:21]
	v_mfma_f32_16x16x32_bf16 v[6:9], v[166:169], v[234:237], v[6:9]
	v_mfma_f32_16x16x32_bf16 v[2:5], v[174:177], v[234:237], v[2:5]
	s_setprio 0
	s_barrier
	v_add_u32_e32 v158, s66, v148
	v_add_u32_e32 v174, s93, v148
	ds_read_b128 v[140:143], v158
	ds_read_b128 v[150:153], v158 offset:1024
	ds_read_b128 v[154:157], v158 offset:2048
	ds_read_b128 v[158:161], v158 offset:3072
	ds_read_b128 v[162:165], v174
	ds_read_b128 v[166:169], v174 offset:1024
	ds_read_b128 v[170:173], v174 offset:2048
	ds_read_b128 v[174:177], v174 offset:3072
	s_add_u32 s28, s28, s6
	s_addc_u32 s29, s29, s7
	s_mov_b32 m0, s82
	v_lshl_add_u64 v[246:247], s[28:29], 0, v[134:135]
	ds_read_b128 v[182:185], v149 offset:32768
	ds_read_b128 v[186:189], v149 offset:33792
	ds_read_b128 v[190:193], v149 offset:34816
	ds_read_b128 v[194:197], v149 offset:35840
	ds_read_b128 v[218:221], v149 offset:36864
	ds_read_b128 v[222:225], v149 offset:37888
	ds_read_b128 v[230:233], v149 offset:38912
	ds_read_b128 v[234:237], v149 offset:39936
	global_load_lds_dwordx4 v[246:247], off
	v_lshl_add_u64 v[246:247], s[28:29], 0, v[132:133]
	s_mov_b32 m0, s83
	s_nop 0
	global_load_lds_dwordx4 v[246:247], off
	s_waitcnt vmcnt(8)
	s_waitcnt lgkmcnt(0)
	s_barrier
	s_setprio 1
	s_waitcnt lgkmcnt(0)
	v_mfma_f32_16x16x32_bf16 v[126:129], v[140:143], v[182:185], v[126:129]
	v_mfma_f32_16x16x32_bf16 v[122:125], v[154:157], v[182:185], v[122:125]
	v_mfma_f32_16x16x32_bf16 v[110:113], v[140:143], v[190:193], v[110:113]
	v_mfma_f32_16x16x32_bf16 v[106:109], v[154:157], v[190:193], v[106:109]
	v_mfma_f32_16x16x32_bf16 v[94:97], v[140:143], v[218:221], v[94:97]
	v_mfma_f32_16x16x32_bf16 v[90:93], v[154:157], v[218:221], v[90:93]
	v_mfma_f32_16x16x32_bf16 v[78:81], v[140:143], v[230:233], v[78:81]
	v_mfma_f32_16x16x32_bf16 v[74:77], v[154:157], v[230:233], v[74:77]
	v_mfma_f32_16x16x32_bf16 v[126:129], v[150:153], v[186:189], v[126:129]
	v_mfma_f32_16x16x32_bf16 v[122:125], v[158:161], v[186:189], v[122:125]
	v_mfma_f32_16x16x32_bf16 v[110:113], v[150:153], v[194:197], v[110:113]
	v_mfma_f32_16x16x32_bf16 v[106:109], v[158:161], v[194:197], v[106:109]
	v_mfma_f32_16x16x32_bf16 v[94:97], v[150:153], v[222:225], v[94:97]
	v_mfma_f32_16x16x32_bf16 v[90:93], v[158:161], v[222:225], v[90:93]
	v_mfma_f32_16x16x32_bf16 v[78:81], v[150:153], v[234:237], v[78:81]
	v_mfma_f32_16x16x32_bf16 v[74:77], v[158:161], v[234:237], v[74:77]
	v_mfma_f32_16x16x32_bf16 v[118:121], v[162:165], v[182:185], v[118:121]
	v_mfma_f32_16x16x32_bf16 v[114:117], v[170:173], v[182:185], v[114:117]
	v_mfma_f32_16x16x32_bf16 v[102:105], v[162:165], v[190:193], v[102:105]
	v_mfma_f32_16x16x32_bf16 v[98:101], v[170:173], v[190:193], v[98:101]
	v_mfma_f32_16x16x32_bf16 v[86:89], v[162:165], v[218:221], v[86:89]
	v_mfma_f32_16x16x32_bf16 v[82:85], v[170:173], v[218:221], v[82:85]
	v_mfma_f32_16x16x32_bf16 v[70:73], v[162:165], v[230:233], v[70:73]
	v_mfma_f32_16x16x32_bf16 v[66:69], v[170:173], v[230:233], v[66:69]
	v_mfma_f32_16x16x32_bf16 v[118:121], v[166:169], v[186:189], v[118:121]
	v_mfma_f32_16x16x32_bf16 v[114:117], v[174:177], v[186:189], v[114:117]
	v_mfma_f32_16x16x32_bf16 v[102:105], v[166:169], v[194:197], v[102:105]
	v_mfma_f32_16x16x32_bf16 v[98:101], v[174:177], v[194:197], v[98:101]
	v_mfma_f32_16x16x32_bf16 v[86:89], v[166:169], v[222:225], v[86:89]
	v_mfma_f32_16x16x32_bf16 v[82:85], v[174:177], v[222:225], v[82:85]
	v_mfma_f32_16x16x32_bf16 v[70:73], v[166:169], v[234:237], v[70:73]
	v_mfma_f32_16x16x32_bf16 v[66:69], v[174:177], v[234:237], v[66:69]
	s_setprio 0
	s_barrier
	s_mov_b32 m0, s67
	v_lshl_add_u64 v[144:145], v[144:145], 0, s[48:49]
	ds_read_b128 v[182:185], v149 offset:49152
	ds_read_b128 v[186:189], v149 offset:50176
	ds_read_b128 v[190:193], v149 offset:51200
	ds_read_b128 v[194:197], v149 offset:52224
	ds_read_b128 v[218:221], v149 offset:53248
	ds_read_b128 v[222:225], v149 offset:54272
	ds_read_b128 v[230:233], v149 offset:55296
	ds_read_b128 v[234:237], v149 offset:56320
	global_load_lds_dwordx4 v[144:145], off
	v_lshl_add_u64 v[144:145], v[198:199], 0, s[48:49]
	s_mov_b32 m0, s96
	s_nop 0
	global_load_lds_dwordx4 v[144:145], off
	v_lshl_add_u64 v[144:145], v[238:239], 0, s[48:49]
	s_mov_b32 m0, s14
	s_nop 0
	global_load_lds_dwordx4 v[144:145], off
	v_lshl_add_u64 v[144:145], v[240:241], 0, s[48:49]
	s_mov_b32 m0, s90
	s_nop 0
	global_load_lds_dwordx4 v[144:145], off
	v_lshl_add_u64 v[144:145], v[242:243], 0, s[48:49]
	s_mov_b32 m0, s51
	s_nop 0
	global_load_lds_dwordx4 v[144:145], off
	v_lshl_add_u64 v[144:145], v[244:245], 0, s[48:49]
	s_mov_b32 m0, s33
	s_nop 0
	global_load_lds_dwordx4 v[144:145], off
	s_waitcnt vmcnt(8)
	s_waitcnt lgkmcnt(0)
	s_barrier
	s_setprio 1
	s_waitcnt lgkmcnt(0)
	v_mfma_f32_16x16x32_bf16 v[62:65], v[140:143], v[182:185], v[62:65]
	v_mfma_f32_16x16x32_bf16 v[58:61], v[154:157], v[182:185], v[58:61]
	v_mfma_f32_16x16x32_bf16 v[46:49], v[140:143], v[190:193], v[46:49]
	v_mfma_f32_16x16x32_bf16 v[42:45], v[154:157], v[190:193], v[42:45]
	v_mfma_f32_16x16x32_bf16 v[30:33], v[140:143], v[218:221], v[30:33]
	v_mfma_f32_16x16x32_bf16 v[26:29], v[154:157], v[218:221], v[26:29]
	v_mfma_f32_16x16x32_bf16 v[14:17], v[140:143], v[230:233], v[14:17]
	v_mfma_f32_16x16x32_bf16 v[10:13], v[154:157], v[230:233], v[10:13]
	v_mfma_f32_16x16x32_bf16 v[62:65], v[150:153], v[186:189], v[62:65]
	v_mfma_f32_16x16x32_bf16 v[58:61], v[158:161], v[186:189], v[58:61]
	v_mfma_f32_16x16x32_bf16 v[46:49], v[150:153], v[194:197], v[46:49]
	v_mfma_f32_16x16x32_bf16 v[42:45], v[158:161], v[194:197], v[42:45]
	v_mfma_f32_16x16x32_bf16 v[30:33], v[150:153], v[222:225], v[30:33]
	v_mfma_f32_16x16x32_bf16 v[26:29], v[158:161], v[222:225], v[26:29]
	v_mfma_f32_16x16x32_bf16 v[14:17], v[150:153], v[234:237], v[14:17]
	v_mfma_f32_16x16x32_bf16 v[10:13], v[158:161], v[234:237], v[10:13]
	v_mfma_f32_16x16x32_bf16 v[54:57], v[162:165], v[182:185], v[54:57]
	v_mfma_f32_16x16x32_bf16 v[50:53], v[170:173], v[182:185], v[50:53]
	v_mfma_f32_16x16x32_bf16 v[38:41], v[162:165], v[190:193], v[38:41]
	v_mfma_f32_16x16x32_bf16 v[34:37], v[170:173], v[190:193], v[34:37]
	v_mfma_f32_16x16x32_bf16 v[22:25], v[162:165], v[218:221], v[22:25]
	v_mfma_f32_16x16x32_bf16 v[18:21], v[170:173], v[218:221], v[18:21]
	v_mfma_f32_16x16x32_bf16 v[6:9], v[162:165], v[230:233], v[6:9]
	v_mfma_f32_16x16x32_bf16 v[2:5], v[170:173], v[230:233], v[2:5]
	v_mfma_f32_16x16x32_bf16 v[54:57], v[166:169], v[186:189], v[54:57]
	v_mfma_f32_16x16x32_bf16 v[50:53], v[174:177], v[186:189], v[50:53]
	v_mfma_f32_16x16x32_bf16 v[38:41], v[166:169], v[194:197], v[38:41]
	v_mfma_f32_16x16x32_bf16 v[34:37], v[174:177], v[194:197], v[34:37]
	v_mfma_f32_16x16x32_bf16 v[22:25], v[166:169], v[222:225], v[22:25]
	v_mfma_f32_16x16x32_bf16 v[18:21], v[174:177], v[222:225], v[18:21]
	v_mfma_f32_16x16x32_bf16 v[6:9], v[166:169], v[234:237], v[6:9]
	v_mfma_f32_16x16x32_bf16 v[2:5], v[174:177], v[234:237], v[2:5]
	s_setprio 0
	s_barrier
	s_add_u32 s46, s46, 0x100
	s_addc_u32 s47, s47, 0
	s_add_u32 s26, s26, 0x100
	s_addc_u32 s27, s27, 0
	s_cmp_ge_i32 s52, s94
	s_mov_b32 s28, s52
	s_cbranch_scc0 .LBB0_1045

.LBB0_1109:
	v_add_u32_e32 v0, s62, v142
	ds_read_b128 v[144:147], v0
	ds_read_b128 v[156:159], v0 offset:1024
	ds_read_b128 v[160:163], v0 offset:2048
	ds_read_b128 v[164:167], v0 offset:3072
	v_add_u32_e32 v0, s65, v142
	ds_read_b128 v[168:171], v0
	ds_read_b128 v[172:175], v0 offset:1024
	ds_read_b128 v[182:185], v0 offset:2048
	ds_read_b128 v[186:189], v0 offset:3072
	s_add_i32 s88, s34, 2
	s_add_u32 s89, s30, 0x80
	s_addc_u32 s35, s31, 0
	s_cmp_eq_u32 s81, s34
	s_cselect_b32 s34, s0, s89
	s_cselect_b32 s35, s1, s35
	s_cselect_b32 s91, s29, s87
	s_cselect_b32 s90, s28, s86
	v_lshl_add_u64 v[148:149], s[30:31], 0, v[140:141]
	s_add_i32 m0, s68, 0xc000
	ds_read_b128 v[190:193], v143
	ds_read_b128 v[194:197], v143 offset:1024
	ds_read_b128 v[218:221], v143 offset:2048
	ds_read_b128 v[222:225], v143 offset:3072
	ds_read_b128 v[230:233], v143 offset:4096
	ds_read_b128 v[234:237], v143 offset:5120
	ds_read_b128 v[238:241], v143 offset:6144
	ds_read_b128 v[242:245], v143 offset:7168
	global_load_lds_dwordx4 v[148:149], off
	v_lshl_add_u64 v[148:149], s[30:31], 0, v[138:139]
	s_add_i32 m0, s68, 0xe000
	s_nop 0
	global_load_lds_dwordx4 v[148:149], off
	s_waitcnt vmcnt(8)
	s_waitcnt lgkmcnt(0)
	s_barrier
	s_setprio 1
	s_waitcnt lgkmcnt(0)
	v_mfma_f32_16x16x32_bf16 v[2:5], v[144:147], v[190:193], v[2:5]
	v_mfma_f32_16x16x32_bf16 v[66:69], v[160:163], v[190:193], v[66:69]
	v_mfma_f32_16x16x32_bf16 v[102:105], v[144:147], v[218:221], v[102:105]
	v_mfma_f32_16x16x32_bf16 v[70:73], v[160:163], v[218:221], v[70:73]
	v_mfma_f32_16x16x32_bf16 v[106:109], v[144:147], v[230:233], v[106:109]
	v_mfma_f32_16x16x32_bf16 v[74:77], v[160:163], v[230:233], v[74:77]
	v_mfma_f32_16x16x32_bf16 v[110:113], v[144:147], v[238:241], v[110:113]
	v_mfma_f32_16x16x32_bf16 v[78:81], v[160:163], v[238:241], v[78:81]
	v_mfma_f32_16x16x32_bf16 v[2:5], v[156:159], v[194:197], v[2:5]
	v_mfma_f32_16x16x32_bf16 v[66:69], v[164:167], v[194:197], v[66:69]
	v_mfma_f32_16x16x32_bf16 v[102:105], v[156:159], v[222:225], v[102:105]
	v_mfma_f32_16x16x32_bf16 v[70:73], v[164:167], v[222:225], v[70:73]
	v_mfma_f32_16x16x32_bf16 v[106:109], v[156:159], v[234:237], v[106:109]
	v_mfma_f32_16x16x32_bf16 v[74:77], v[164:167], v[234:237], v[74:77]
	v_mfma_f32_16x16x32_bf16 v[110:113], v[156:159], v[242:245], v[110:113]
	v_mfma_f32_16x16x32_bf16 v[78:81], v[164:167], v[242:245], v[78:81]
	v_mfma_f32_16x16x32_bf16 v[34:37], v[168:171], v[190:193], v[34:37]
	v_mfma_f32_16x16x32_bf16 v[130:133], v[182:185], v[190:193], v[130:133]
	v_mfma_f32_16x16x32_bf16 v[38:41], v[168:171], v[218:221], v[38:41]
	v_mfma_f32_16x16x32_bf16 v[6:9], v[182:185], v[218:221], v[6:9]
	v_mfma_f32_16x16x32_bf16 v[42:45], v[168:171], v[230:233], v[42:45]
	v_mfma_f32_16x16x32_bf16 v[10:13], v[182:185], v[230:233], v[10:13]
	v_mfma_f32_16x16x32_bf16 v[46:49], v[168:171], v[238:241], v[46:49]
	v_mfma_f32_16x16x32_bf16 v[14:17], v[182:185], v[238:241], v[14:17]
	v_mfma_f32_16x16x32_bf16 v[34:37], v[172:175], v[194:197], v[34:37]
	v_mfma_f32_16x16x32_bf16 v[130:133], v[186:189], v[194:197], v[130:133]
	v_mfma_f32_16x16x32_bf16 v[38:41], v[172:175], v[222:225], v[38:41]
	v_mfma_f32_16x16x32_bf16 v[6:9], v[186:189], v[222:225], v[6:9]
	v_mfma_f32_16x16x32_bf16 v[42:45], v[172:175], v[234:237], v[42:45]
	v_mfma_f32_16x16x32_bf16 v[10:13], v[186:189], v[234:237], v[10:13]
	v_mfma_f32_16x16x32_bf16 v[46:49], v[172:175], v[242:245], v[46:49]
	v_mfma_f32_16x16x32_bf16 v[14:17], v[186:189], v[242:245], v[14:17]
	s_setprio 0
	s_barrier
	s_mov_b32 m0, s63
	v_lshl_add_u64 v[148:149], s[90:91], 0, v[134:135]
	v_lshl_add_u64 v[152:153], s[90:91], 0, v[94:95]
	s_add_u32 s90, s90, s12
	ds_read_b128 v[190:193], v143 offset:16384
	ds_read_b128 v[194:197], v143 offset:17408
	ds_read_b128 v[218:221], v143 offset:18432
	ds_read_b128 v[222:225], v143 offset:19456
	ds_read_b128 v[230:233], v143 offset:20480
	ds_read_b128 v[234:237], v143 offset:21504
	ds_read_b128 v[238:241], v143 offset:22528
	ds_read_b128 v[242:245], v143 offset:23552
	global_load_lds_dwordx4 v[148:149], off
	s_mov_b32 m0, s64
	s_addc_u32 s91, s91, s13
	global_load_lds_dwordx4 v[152:153], off
	v_lshl_add_u64 v[176:177], s[90:91], 0, v[134:135]
	s_mov_b32 m0, s66
	v_lshl_add_u64 v[198:199], s[90:91], 0, v[94:95]
	global_load_lds_dwordx4 v[176:177], off
	s_mov_b32 m0, s67
	v_lshl_add_u64 v[246:247], s[34:35], 0, v[136:137]
	global_load_lds_dwordx4 v[198:199], off
	s_mov_b32 m0, s68
	v_lshl_add_u64 v[248:249], s[34:35], 0, v[96:97]
	global_load_lds_dwordx4 v[246:247], off
	s_mov_b32 m0, s69
	s_nop 0
	global_load_lds_dwordx4 v[248:249], off
	s_waitcnt vmcnt(8)
	s_waitcnt lgkmcnt(0)
	s_barrier
	s_setprio 1
	s_waitcnt lgkmcnt(0)
	v_mfma_f32_16x16x32_bf16 v[114:117], v[144:147], v[190:193], v[114:117]
	v_mfma_f32_16x16x32_bf16 v[82:85], v[160:163], v[190:193], v[82:85]
	v_mfma_f32_16x16x32_bf16 v[118:121], v[144:147], v[218:221], v[118:121]
	v_mfma_f32_16x16x32_bf16 v[86:89], v[160:163], v[218:221], v[86:89]
	v_mfma_f32_16x16x32_bf16 v[122:125], v[144:147], v[230:233], v[122:125]
	v_mfma_f32_16x16x32_bf16 v[90:93], v[160:163], v[230:233], v[90:93]
	v_mfma_f32_16x16x32_bf16 v[126:129], v[144:147], v[238:241], v[126:129]
	v_mfma_f32_16x16x32_bf16 v[98:101], v[160:163], v[238:241], v[98:101]
	v_mfma_f32_16x16x32_bf16 v[114:117], v[156:159], v[194:197], v[114:117]
	v_mfma_f32_16x16x32_bf16 v[82:85], v[164:167], v[194:197], v[82:85]
	v_mfma_f32_16x16x32_bf16 v[118:121], v[156:159], v[222:225], v[118:121]
	v_mfma_f32_16x16x32_bf16 v[86:89], v[164:167], v[222:225], v[86:89]
	v_mfma_f32_16x16x32_bf16 v[122:125], v[156:159], v[234:237], v[122:125]
	v_mfma_f32_16x16x32_bf16 v[90:93], v[164:167], v[234:237], v[90:93]
	v_mfma_f32_16x16x32_bf16 v[126:129], v[156:159], v[242:245], v[126:129]
	v_mfma_f32_16x16x32_bf16 v[98:101], v[164:167], v[242:245], v[98:101]
	v_mfma_f32_16x16x32_bf16 v[50:53], v[168:171], v[190:193], v[50:53]
	v_mfma_f32_16x16x32_bf16 v[18:21], v[182:185], v[190:193], v[18:21]
	v_mfma_f32_16x16x32_bf16 v[54:57], v[168:171], v[218:221], v[54:57]
	v_mfma_f32_16x16x32_bf16 v[22:25], v[182:185], v[218:221], v[22:25]
	v_mfma_f32_16x16x32_bf16 v[58:61], v[168:171], v[230:233], v[58:61]
	v_mfma_f32_16x16x32_bf16 v[26:29], v[182:185], v[230:233], v[26:29]
	v_mfma_f32_16x16x32_bf16 v[62:65], v[168:171], v[238:241], v[62:65]
	v_mfma_f32_16x16x32_bf16 v[30:33], v[182:185], v[238:241], v[30:33]
	v_mfma_f32_16x16x32_bf16 v[50:53], v[172:175], v[194:197], v[50:53]
	v_mfma_f32_16x16x32_bf16 v[18:21], v[186:189], v[194:197], v[18:21]
	v_mfma_f32_16x16x32_bf16 v[54:57], v[172:175], v[222:225], v[54:57]
	v_mfma_f32_16x16x32_bf16 v[22:25], v[186:189], v[222:225], v[22:25]
	v_mfma_f32_16x16x32_bf16 v[58:61], v[172:175], v[234:237], v[58:61]
	v_mfma_f32_16x16x32_bf16 v[26:29], v[186:189], v[234:237], v[26:29]
	v_mfma_f32_16x16x32_bf16 v[62:65], v[172:175], v[242:245], v[62:65]
	v_mfma_f32_16x16x32_bf16 v[30:33], v[186:189], v[242:245], v[30:33]
	s_setprio 0
	s_barrier
	v_add_u32_e32 v0, s72, v142
	ds_read_b128 v[144:147], v0
	ds_read_b128 v[156:159], v0 offset:1024
	ds_read_b128 v[160:163], v0 offset:2048
	ds_read_b128 v[164:167], v0 offset:3072
	v_add_u32_e32 v0, s77, v142
	ds_read_b128 v[168:171], v0
	ds_read_b128 v[172:175], v0 offset:1024
	ds_read_b128 v[182:185], v0 offset:2048
	ds_read_b128 v[186:189], v0 offset:3072
	s_add_u32 s34, s34, s10
	s_addc_u32 s35, s35, s11
	s_mov_b32 m0, s70
	v_lshl_add_u64 v[250:251], s[34:35], 0, v[136:137]
	ds_read_b128 v[190:193], v143 offset:32768
	ds_read_b128 v[194:197], v143 offset:33792
	ds_read_b128 v[218:221], v143 offset:34816
	ds_read_b128 v[222:225], v143 offset:35840
	ds_read_b128 v[230:233], v143 offset:36864
	ds_read_b128 v[234:237], v143 offset:37888
	ds_read_b128 v[238:241], v143 offset:38912
	ds_read_b128 v[242:245], v143 offset:39936
	global_load_lds_dwordx4 v[250:251], off
	v_lshl_add_u64 v[250:251], s[34:35], 0, v[96:97]
	s_mov_b32 m0, s71
	s_nop 0
	global_load_lds_dwordx4 v[250:251], off
	s_waitcnt vmcnt(8)
	s_waitcnt lgkmcnt(0)
	s_barrier
	s_setprio 1
	s_waitcnt lgkmcnt(0)
	v_mfma_f32_16x16x32_bf16 v[2:5], v[144:147], v[190:193], v[2:5]
	v_mfma_f32_16x16x32_bf16 v[66:69], v[160:163], v[190:193], v[66:69]
	v_mfma_f32_16x16x32_bf16 v[102:105], v[144:147], v[218:221], v[102:105]
	v_mfma_f32_16x16x32_bf16 v[70:73], v[160:163], v[218:221], v[70:73]
	v_mfma_f32_16x16x32_bf16 v[106:109], v[144:147], v[230:233], v[106:109]
	v_mfma_f32_16x16x32_bf16 v[74:77], v[160:163], v[230:233], v[74:77]
	v_mfma_f32_16x16x32_bf16 v[110:113], v[144:147], v[238:241], v[110:113]
	v_mfma_f32_16x16x32_bf16 v[78:81], v[160:163], v[238:241], v[78:81]
	v_mfma_f32_16x16x32_bf16 v[2:5], v[156:159], v[194:197], v[2:5]
	v_mfma_f32_16x16x32_bf16 v[66:69], v[164:167], v[194:197], v[66:69]
	v_mfma_f32_16x16x32_bf16 v[102:105], v[156:159], v[222:225], v[102:105]
	v_mfma_f32_16x16x32_bf16 v[70:73], v[164:167], v[222:225], v[70:73]
	v_mfma_f32_16x16x32_bf16 v[106:109], v[156:159], v[234:237], v[106:109]
	v_mfma_f32_16x16x32_bf16 v[74:77], v[164:167], v[234:237], v[74:77]
	v_mfma_f32_16x16x32_bf16 v[110:113], v[156:159], v[242:245], v[110:113]
	v_mfma_f32_16x16x32_bf16 v[78:81], v[164:167], v[242:245], v[78:81]
	v_mfma_f32_16x16x32_bf16 v[34:37], v[168:171], v[190:193], v[34:37]
	v_mfma_f32_16x16x32_bf16 v[130:133], v[182:185], v[190:193], v[130:133]
	v_mfma_f32_16x16x32_bf16 v[38:41], v[168:171], v[218:221], v[38:41]
	v_mfma_f32_16x16x32_bf16 v[6:9], v[182:185], v[218:221], v[6:9]
	v_mfma_f32_16x16x32_bf16 v[42:45], v[168:171], v[230:233], v[42:45]
	v_mfma_f32_16x16x32_bf16 v[10:13], v[182:185], v[230:233], v[10:13]
	v_mfma_f32_16x16x32_bf16 v[46:49], v[168:171], v[238:241], v[46:49]
	v_mfma_f32_16x16x32_bf16 v[14:17], v[182:185], v[238:241], v[14:17]
	v_mfma_f32_16x16x32_bf16 v[34:37], v[172:175], v[194:197], v[34:37]
	v_mfma_f32_16x16x32_bf16 v[130:133], v[186:189], v[194:197], v[130:133]
	v_mfma_f32_16x16x32_bf16 v[38:41], v[172:175], v[222:225], v[38:41]
	v_mfma_f32_16x16x32_bf16 v[6:9], v[186:189], v[222:225], v[6:9]
	v_mfma_f32_16x16x32_bf16 v[42:45], v[172:175], v[234:237], v[42:45]
	v_mfma_f32_16x16x32_bf16 v[10:13], v[186:189], v[234:237], v[10:13]
	v_mfma_f32_16x16x32_bf16 v[46:49], v[172:175], v[242:245], v[46:49]
	v_mfma_f32_16x16x32_bf16 v[14:17], v[186:189], v[242:245], v[14:17]
	s_setprio 0
	s_barrier
	s_mov_b32 m0, s73
	v_lshl_add_u64 v[148:149], v[148:149], 0, s[48:49]
	ds_read_b128 v[190:193], v143 offset:49152
	ds_read_b128 v[194:197], v143 offset:50176
	ds_read_b128 v[218:221], v143 offset:51200
	ds_read_b128 v[222:225], v143 offset:52224
	ds_read_b128 v[230:233], v143 offset:53248
	ds_read_b128 v[234:237], v143 offset:54272
	ds_read_b128 v[238:241], v143 offset:55296
	ds_read_b128 v[242:245], v143 offset:56320
	global_load_lds_dwordx4 v[148:149], off
	v_lshl_add_u64 v[148:149], v[152:153], 0, s[48:49]
	s_mov_b32 m0, s74
	s_nop 0
	global_load_lds_dwordx4 v[148:149], off
	v_lshl_add_u64 v[148:149], v[176:177], 0, s[48:49]
	s_mov_b32 m0, s78
	s_nop 0
	global_load_lds_dwordx4 v[148:149], off
	v_lshl_add_u64 v[148:149], v[198:199], 0, s[48:49]
	s_mov_b32 m0, s79
	s_nop 0
	global_load_lds_dwordx4 v[148:149], off
	v_lshl_add_u64 v[148:149], v[246:247], 0, s[48:49]
	s_mov_b32 m0, s75
	s_nop 0
	global_load_lds_dwordx4 v[148:149], off
	v_lshl_add_u64 v[148:149], v[248:249], 0, s[48:49]
	s_mov_b32 m0, s76
	s_nop 0
	global_load_lds_dwordx4 v[148:149], off
	s_waitcnt vmcnt(8)
	s_waitcnt lgkmcnt(0)
	s_barrier
	s_setprio 1
	s_waitcnt lgkmcnt(0)
	v_mfma_f32_16x16x32_bf16 v[114:117], v[144:147], v[190:193], v[114:117]
	v_mfma_f32_16x16x32_bf16 v[82:85], v[160:163], v[190:193], v[82:85]
	v_mfma_f32_16x16x32_bf16 v[118:121], v[144:147], v[218:221], v[118:121]
	v_mfma_f32_16x16x32_bf16 v[86:89], v[160:163], v[218:221], v[86:89]
	v_mfma_f32_16x16x32_bf16 v[122:125], v[144:147], v[230:233], v[122:125]
	v_mfma_f32_16x16x32_bf16 v[90:93], v[160:163], v[230:233], v[90:93]
	v_mfma_f32_16x16x32_bf16 v[126:129], v[144:147], v[238:241], v[126:129]
	v_mfma_f32_16x16x32_bf16 v[98:101], v[160:163], v[238:241], v[98:101]
	v_mfma_f32_16x16x32_bf16 v[114:117], v[156:159], v[194:197], v[114:117]
	v_mfma_f32_16x16x32_bf16 v[82:85], v[164:167], v[194:197], v[82:85]
	v_mfma_f32_16x16x32_bf16 v[118:121], v[156:159], v[222:225], v[118:121]
	v_mfma_f32_16x16x32_bf16 v[86:89], v[164:167], v[222:225], v[86:89]
	v_mfma_f32_16x16x32_bf16 v[122:125], v[156:159], v[234:237], v[122:125]
	v_mfma_f32_16x16x32_bf16 v[90:93], v[164:167], v[234:237], v[90:93]
	v_mfma_f32_16x16x32_bf16 v[126:129], v[156:159], v[242:245], v[126:129]
	v_mfma_f32_16x16x32_bf16 v[98:101], v[164:167], v[242:245], v[98:101]
	v_mfma_f32_16x16x32_bf16 v[50:53], v[168:171], v[190:193], v[50:53]
	v_mfma_f32_16x16x32_bf16 v[18:21], v[182:185], v[190:193], v[18:21]
	v_mfma_f32_16x16x32_bf16 v[54:57], v[168:171], v[218:221], v[54:57]
	v_mfma_f32_16x16x32_bf16 v[22:25], v[182:185], v[218:221], v[22:25]
	v_mfma_f32_16x16x32_bf16 v[58:61], v[168:171], v[230:233], v[58:61]
	v_mfma_f32_16x16x32_bf16 v[26:29], v[182:185], v[230:233], v[26:29]
	v_mfma_f32_16x16x32_bf16 v[62:65], v[168:171], v[238:241], v[62:65]
	v_mfma_f32_16x16x32_bf16 v[30:33], v[182:185], v[238:241], v[30:33]
	v_mfma_f32_16x16x32_bf16 v[50:53], v[172:175], v[194:197], v[50:53]
	v_mfma_f32_16x16x32_bf16 v[18:21], v[186:189], v[194:197], v[18:21]
	v_mfma_f32_16x16x32_bf16 v[54:57], v[172:175], v[222:225], v[54:57]
	v_mfma_f32_16x16x32_bf16 v[22:25], v[186:189], v[222:225], v[22:25]
	v_mfma_f32_16x16x32_bf16 v[58:61], v[172:175], v[234:237], v[58:61]
	v_mfma_f32_16x16x32_bf16 v[26:29], v[186:189], v[234:237], v[26:29]
	v_mfma_f32_16x16x32_bf16 v[62:65], v[172:175], v[242:245], v[62:65]
	v_mfma_f32_16x16x32_bf16 v[30:33], v[186:189], v[242:245], v[30:33]
	s_setprio 0
	s_barrier
	s_add_u32 s86, s86, 0x100
	s_addc_u32 s87, s87, 0
	s_add_u32 s30, s30, 0x100
	s_addc_u32 s31, s31, 0
	s_cmp_ge_i32 s88, s80
	s_mov_b32 s34, s88
	s_cbranch_scc0 .LBB0_1109

.LBB0_1274:
	v_add_u32_e32 v0, s59, v218
	ds_read_b128 v[74:77], v0
	ds_read_b128 v[78:81], v0 offset:1024
	ds_read_b128 v[82:85], v0 offset:2048
	ds_read_b128 v[86:89], v0 offset:3072
	v_add_u32_e32 v0, s62, v218
	ds_read_b128 v[98:101], v0
	ds_read_b128 v[102:105], v0 offset:1024
	ds_read_b128 v[106:109], v0 offset:2048
	ds_read_b128 v[110:113], v0 offset:3072
	s_add_i32 s35, s6, 2
	s_add_u32 s68, s4, 0x80
	s_addc_u32 s7, s5, 0
	s_cmp_eq_u32 s85, s6
	s_cselect_b32 s6, s0, s68
	s_cselect_b32 s7, s1, s7
	s_cselect_b32 s69, s31, s34
	s_cselect_b32 s68, s30, s9
	v_lshl_add_u64 v[198:199], s[4:5], 0, v[192:193]
	s_add_i32 m0, s65, 0xc000
	ds_read_b128 v[162:165], v219
	ds_read_b128 v[166:169], v219 offset:1024
	ds_read_b128 v[170:173], v219 offset:2048
	ds_read_b128 v[174:177], v219 offset:3072
	ds_read_b128 v[194:197], v219 offset:4096
	ds_read_b128 v[220:223], v219 offset:5120
	ds_read_b128 v[230:233], v219 offset:6144
	ds_read_b128 v[234:237], v219 offset:7168
	global_load_lds_dwordx4 v[198:199], off
	v_lshl_add_u64 v[198:199], s[4:5], 0, v[190:191]
	s_add_i32 m0, s65, 0xe000
	s_nop 0
	global_load_lds_dwordx4 v[198:199], off
	s_waitcnt vmcnt(8)
	s_waitcnt lgkmcnt(0)
	s_barrier
	s_setprio 1
	s_waitcnt lgkmcnt(0)
	v_mfma_f32_16x16x32_bf16 v[154:157], v[74:77], v[162:165], v[154:157]
	v_mfma_f32_16x16x32_bf16 v[158:161], v[82:85], v[162:165], v[158:161]
	v_mfma_f32_16x16x32_bf16 v[142:145], v[74:77], v[170:173], v[142:145]
	v_mfma_f32_16x16x32_bf16 v[134:137], v[82:85], v[170:173], v[134:137]
	v_mfma_f32_16x16x32_bf16 v[126:129], v[74:77], v[194:197], v[126:129]
	v_mfma_f32_16x16x32_bf16 v[118:121], v[82:85], v[194:197], v[118:121]
	v_mfma_f32_16x16x32_bf16 v[94:97], v[74:77], v[230:233], v[94:97]
	v_mfma_f32_16x16x32_bf16 v[70:73], v[82:85], v[230:233], v[70:73]
	v_mfma_f32_16x16x32_bf16 v[154:157], v[78:81], v[166:169], v[154:157]
	v_mfma_f32_16x16x32_bf16 v[158:161], v[86:89], v[166:169], v[158:161]
	v_mfma_f32_16x16x32_bf16 v[142:145], v[78:81], v[174:177], v[142:145]
	v_mfma_f32_16x16x32_bf16 v[134:137], v[86:89], v[174:177], v[134:137]
	v_mfma_f32_16x16x32_bf16 v[126:129], v[78:81], v[220:223], v[126:129]
	v_mfma_f32_16x16x32_bf16 v[118:121], v[86:89], v[220:223], v[118:121]
	v_mfma_f32_16x16x32_bf16 v[94:97], v[78:81], v[234:237], v[94:97]
	v_mfma_f32_16x16x32_bf16 v[70:73], v[86:89], v[234:237], v[70:73]
	v_mfma_f32_16x16x32_bf16 v[150:153], v[98:101], v[162:165], v[150:153]
	v_mfma_f32_16x16x32_bf16 v[146:149], v[106:109], v[162:165], v[146:149]
	v_mfma_f32_16x16x32_bf16 v[138:141], v[98:101], v[170:173], v[138:141]
	v_mfma_f32_16x16x32_bf16 v[130:133], v[106:109], v[170:173], v[130:133]
	v_mfma_f32_16x16x32_bf16 v[122:125], v[98:101], v[194:197], v[122:125]
	v_mfma_f32_16x16x32_bf16 v[114:117], v[106:109], v[194:197], v[114:117]
	v_mfma_f32_16x16x32_bf16 v[90:93], v[98:101], v[230:233], v[90:93]
	v_mfma_f32_16x16x32_bf16 v[66:69], v[106:109], v[230:233], v[66:69]
	v_mfma_f32_16x16x32_bf16 v[150:153], v[102:105], v[166:169], v[150:153]
	v_mfma_f32_16x16x32_bf16 v[146:149], v[110:113], v[166:169], v[146:149]
	v_mfma_f32_16x16x32_bf16 v[138:141], v[102:105], v[174:177], v[138:141]
	v_mfma_f32_16x16x32_bf16 v[130:133], v[110:113], v[174:177], v[130:133]
	v_mfma_f32_16x16x32_bf16 v[122:125], v[102:105], v[220:223], v[122:125]
	v_mfma_f32_16x16x32_bf16 v[114:117], v[110:113], v[220:223], v[114:117]
	v_mfma_f32_16x16x32_bf16 v[90:93], v[102:105], v[234:237], v[90:93]
	v_mfma_f32_16x16x32_bf16 v[66:69], v[110:113], v[234:237], v[66:69]
	s_setprio 0
	s_barrier
	s_mov_b32 m0, s60
	v_lshl_add_u64 v[198:199], s[68:69], 0, v[186:187]
	v_lshl_add_u64 v[224:225], s[68:69], 0, v[182:183]
	s_add_u32 s68, s68, s18
	ds_read_b128 v[162:165], v219 offset:16384
	ds_read_b128 v[166:169], v219 offset:17408
	ds_read_b128 v[170:173], v219 offset:18432
	ds_read_b128 v[174:177], v219 offset:19456
	ds_read_b128 v[194:197], v219 offset:20480
	ds_read_b128 v[220:223], v219 offset:21504
	ds_read_b128 v[230:233], v219 offset:22528
	ds_read_b128 v[234:237], v219 offset:23552
	global_load_lds_dwordx4 v[198:199], off
	s_mov_b32 m0, s61
	s_addc_u32 s69, s69, s19
	global_load_lds_dwordx4 v[224:225], off
	v_lshl_add_u64 v[238:239], s[68:69], 0, v[186:187]
	s_mov_b32 m0, s63
	v_lshl_add_u64 v[240:241], s[68:69], 0, v[182:183]
	global_load_lds_dwordx4 v[238:239], off
	s_mov_b32 m0, s64
	v_lshl_add_u64 v[242:243], s[6:7], 0, v[188:189]
	global_load_lds_dwordx4 v[240:241], off
	s_mov_b32 m0, s65
	v_lshl_add_u64 v[244:245], s[6:7], 0, v[184:185]
	global_load_lds_dwordx4 v[242:243], off
	s_mov_b32 m0, s66
	s_nop 0
	global_load_lds_dwordx4 v[244:245], off
	s_waitcnt vmcnt(8)
	s_waitcnt lgkmcnt(0)
	s_barrier
	s_setprio 1
	s_waitcnt lgkmcnt(0)
	v_mfma_f32_16x16x32_bf16 v[62:65], v[74:77], v[162:165], v[62:65]
	v_mfma_f32_16x16x32_bf16 v[54:57], v[82:85], v[162:165], v[54:57]
	v_mfma_f32_16x16x32_bf16 v[46:49], v[74:77], v[170:173], v[46:49]
	v_mfma_f32_16x16x32_bf16 v[38:41], v[82:85], v[170:173], v[38:41]
	v_mfma_f32_16x16x32_bf16 v[30:33], v[74:77], v[194:197], v[30:33]
	v_mfma_f32_16x16x32_bf16 v[22:25], v[82:85], v[194:197], v[22:25]
	v_mfma_f32_16x16x32_bf16 v[6:9], v[74:77], v[230:233], v[6:9]
	v_mfma_f32_16x16x32_bf16 v[2:5], v[82:85], v[230:233], v[2:5]
	v_mfma_f32_16x16x32_bf16 v[62:65], v[78:81], v[166:169], v[62:65]
	v_mfma_f32_16x16x32_bf16 v[54:57], v[86:89], v[166:169], v[54:57]
	v_mfma_f32_16x16x32_bf16 v[46:49], v[78:81], v[174:177], v[46:49]
	v_mfma_f32_16x16x32_bf16 v[38:41], v[86:89], v[174:177], v[38:41]
	v_mfma_f32_16x16x32_bf16 v[30:33], v[78:81], v[220:223], v[30:33]
	v_mfma_f32_16x16x32_bf16 v[22:25], v[86:89], v[220:223], v[22:25]
	v_mfma_f32_16x16x32_bf16 v[6:9], v[78:81], v[234:237], v[6:9]
	v_mfma_f32_16x16x32_bf16 v[2:5], v[86:89], v[234:237], v[2:5]
	v_mfma_f32_16x16x32_bf16 v[58:61], v[98:101], v[162:165], v[58:61]
	v_mfma_f32_16x16x32_bf16 v[50:53], v[106:109], v[162:165], v[50:53]
	v_mfma_f32_16x16x32_bf16 v[42:45], v[98:101], v[170:173], v[42:45]
	v_mfma_f32_16x16x32_bf16 v[34:37], v[106:109], v[170:173], v[34:37]
	v_mfma_f32_16x16x32_bf16 v[26:29], v[98:101], v[194:197], v[26:29]
	v_mfma_f32_16x16x32_bf16 v[18:21], v[106:109], v[194:197], v[18:21]
	v_mfma_f32_16x16x32_bf16 v[14:17], v[98:101], v[230:233], v[14:17]
	v_mfma_f32_16x16x32_bf16 v[10:13], v[106:109], v[230:233], v[10:13]
	v_mfma_f32_16x16x32_bf16 v[58:61], v[102:105], v[166:169], v[58:61]
	v_mfma_f32_16x16x32_bf16 v[50:53], v[110:113], v[166:169], v[50:53]
	v_mfma_f32_16x16x32_bf16 v[42:45], v[102:105], v[174:177], v[42:45]
	v_mfma_f32_16x16x32_bf16 v[34:37], v[110:113], v[174:177], v[34:37]
	v_mfma_f32_16x16x32_bf16 v[26:29], v[102:105], v[220:223], v[26:29]
	v_mfma_f32_16x16x32_bf16 v[18:21], v[110:113], v[220:223], v[18:21]
	v_mfma_f32_16x16x32_bf16 v[14:17], v[102:105], v[234:237], v[14:17]
	v_mfma_f32_16x16x32_bf16 v[10:13], v[110:113], v[234:237], v[10:13]
	s_setprio 0
	s_barrier
	v_add_u32_e32 v0, s77, v218
	ds_read_b128 v[74:77], v0
	ds_read_b128 v[78:81], v0 offset:1024
	ds_read_b128 v[82:85], v0 offset:2048
	ds_read_b128 v[86:89], v0 offset:3072
	v_add_u32_e32 v0, s82, v218
	ds_read_b128 v[98:101], v0
	ds_read_b128 v[102:105], v0 offset:1024
	ds_read_b128 v[106:109], v0 offset:2048
	ds_read_b128 v[110:113], v0 offset:3072
	s_add_u32 s6, s6, s12
	s_addc_u32 s7, s7, s13
	s_mov_b32 m0, s67
	v_lshl_add_u64 v[246:247], s[6:7], 0, v[188:189]
	ds_read_b128 v[162:165], v219 offset:32768
	ds_read_b128 v[166:169], v219 offset:33792
	ds_read_b128 v[170:173], v219 offset:34816
	ds_read_b128 v[174:177], v219 offset:35840
	ds_read_b128 v[194:197], v219 offset:36864
	ds_read_b128 v[220:223], v219 offset:37888
	ds_read_b128 v[230:233], v219 offset:38912
	ds_read_b128 v[234:237], v219 offset:39936
	global_load_lds_dwordx4 v[246:247], off
	v_lshl_add_u64 v[246:247], s[6:7], 0, v[184:185]
	s_mov_b32 m0, s74
	s_nop 0
	global_load_lds_dwordx4 v[246:247], off
	s_waitcnt vmcnt(8)
	s_waitcnt lgkmcnt(0)
	s_barrier
	s_setprio 1
	s_waitcnt lgkmcnt(0)
	v_mfma_f32_16x16x32_bf16 v[154:157], v[74:77], v[162:165], v[154:157]
	v_mfma_f32_16x16x32_bf16 v[158:161], v[82:85], v[162:165], v[158:161]
	v_mfma_f32_16x16x32_bf16 v[142:145], v[74:77], v[170:173], v[142:145]
	v_mfma_f32_16x16x32_bf16 v[134:137], v[82:85], v[170:173], v[134:137]
	v_mfma_f32_16x16x32_bf16 v[126:129], v[74:77], v[194:197], v[126:129]
	v_mfma_f32_16x16x32_bf16 v[118:121], v[82:85], v[194:197], v[118:121]
	v_mfma_f32_16x16x32_bf16 v[94:97], v[74:77], v[230:233], v[94:97]
	v_mfma_f32_16x16x32_bf16 v[70:73], v[82:85], v[230:233], v[70:73]
	v_mfma_f32_16x16x32_bf16 v[154:157], v[78:81], v[166:169], v[154:157]
	v_mfma_f32_16x16x32_bf16 v[158:161], v[86:89], v[166:169], v[158:161]
	v_mfma_f32_16x16x32_bf16 v[142:145], v[78:81], v[174:177], v[142:145]
	v_mfma_f32_16x16x32_bf16 v[134:137], v[86:89], v[174:177], v[134:137]
	v_mfma_f32_16x16x32_bf16 v[126:129], v[78:81], v[220:223], v[126:129]
	v_mfma_f32_16x16x32_bf16 v[118:121], v[86:89], v[220:223], v[118:121]
	v_mfma_f32_16x16x32_bf16 v[94:97], v[78:81], v[234:237], v[94:97]
	v_mfma_f32_16x16x32_bf16 v[70:73], v[86:89], v[234:237], v[70:73]
	v_mfma_f32_16x16x32_bf16 v[150:153], v[98:101], v[162:165], v[150:153]
	v_mfma_f32_16x16x32_bf16 v[146:149], v[106:109], v[162:165], v[146:149]
	v_mfma_f32_16x16x32_bf16 v[138:141], v[98:101], v[170:173], v[138:141]
	v_mfma_f32_16x16x32_bf16 v[130:133], v[106:109], v[170:173], v[130:133]
	v_mfma_f32_16x16x32_bf16 v[122:125], v[98:101], v[194:197], v[122:125]
	v_mfma_f32_16x16x32_bf16 v[114:117], v[106:109], v[194:197], v[114:117]
	v_mfma_f32_16x16x32_bf16 v[90:93], v[98:101], v[230:233], v[90:93]
	v_mfma_f32_16x16x32_bf16 v[66:69], v[106:109], v[230:233], v[66:69]
	v_mfma_f32_16x16x32_bf16 v[150:153], v[102:105], v[166:169], v[150:153]
	v_mfma_f32_16x16x32_bf16 v[146:149], v[110:113], v[166:169], v[146:149]
	v_mfma_f32_16x16x32_bf16 v[138:141], v[102:105], v[174:177], v[138:141]
	v_mfma_f32_16x16x32_bf16 v[130:133], v[110:113], v[174:177], v[130:133]
	v_mfma_f32_16x16x32_bf16 v[122:125], v[102:105], v[220:223], v[122:125]
	v_mfma_f32_16x16x32_bf16 v[114:117], v[110:113], v[220:223], v[114:117]
	v_mfma_f32_16x16x32_bf16 v[90:93], v[102:105], v[234:237], v[90:93]
	v_mfma_f32_16x16x32_bf16 v[66:69], v[110:113], v[234:237], v[66:69]
	s_setprio 0
	s_barrier
	s_mov_b32 m0, s78
	v_lshl_add_u64 v[198:199], v[198:199], 0, s[48:49]
	ds_read_b128 v[162:165], v219 offset:49152
	ds_read_b128 v[166:169], v219 offset:50176
	ds_read_b128 v[170:173], v219 offset:51200
	ds_read_b128 v[174:177], v219 offset:52224
	ds_read_b128 v[194:197], v219 offset:53248
	ds_read_b128 v[220:223], v219 offset:54272
	ds_read_b128 v[230:233], v219 offset:55296
	ds_read_b128 v[234:237], v219 offset:56320
	global_load_lds_dwordx4 v[198:199], off
	v_lshl_add_u64 v[198:199], v[224:225], 0, s[48:49]
	s_mov_b32 m0, s79
	s_nop 0
	global_load_lds_dwordx4 v[198:199], off
	v_lshl_add_u64 v[198:199], v[238:239], 0, s[48:49]
	s_mov_b32 m0, s83
	s_nop 0
	global_load_lds_dwordx4 v[198:199], off
	v_lshl_add_u64 v[198:199], v[240:241], 0, s[48:49]
	s_mov_b32 m0, s84
	s_nop 0
	global_load_lds_dwordx4 v[198:199], off
	v_lshl_add_u64 v[198:199], v[242:243], 0, s[48:49]
	s_mov_b32 m0, s80
	s_nop 0
	global_load_lds_dwordx4 v[198:199], off
	v_lshl_add_u64 v[198:199], v[244:245], 0, s[48:49]
	s_mov_b32 m0, s81
	s_nop 0
	global_load_lds_dwordx4 v[198:199], off
	s_waitcnt vmcnt(8)
	s_waitcnt lgkmcnt(0)
	s_barrier
	s_setprio 1
	s_waitcnt lgkmcnt(0)
	v_mfma_f32_16x16x32_bf16 v[62:65], v[74:77], v[162:165], v[62:65]
	v_mfma_f32_16x16x32_bf16 v[54:57], v[82:85], v[162:165], v[54:57]
	v_mfma_f32_16x16x32_bf16 v[46:49], v[74:77], v[170:173], v[46:49]
	v_mfma_f32_16x16x32_bf16 v[38:41], v[82:85], v[170:173], v[38:41]
	v_mfma_f32_16x16x32_bf16 v[30:33], v[74:77], v[194:197], v[30:33]
	v_mfma_f32_16x16x32_bf16 v[22:25], v[82:85], v[194:197], v[22:25]
	v_mfma_f32_16x16x32_bf16 v[6:9], v[74:77], v[230:233], v[6:9]
	v_mfma_f32_16x16x32_bf16 v[2:5], v[82:85], v[230:233], v[2:5]
	v_mfma_f32_16x16x32_bf16 v[62:65], v[78:81], v[166:169], v[62:65]
	v_mfma_f32_16x16x32_bf16 v[54:57], v[86:89], v[166:169], v[54:57]
	v_mfma_f32_16x16x32_bf16 v[46:49], v[78:81], v[174:177], v[46:49]
	v_mfma_f32_16x16x32_bf16 v[38:41], v[86:89], v[174:177], v[38:41]
	v_mfma_f32_16x16x32_bf16 v[30:33], v[78:81], v[220:223], v[30:33]
	v_mfma_f32_16x16x32_bf16 v[22:25], v[86:89], v[220:223], v[22:25]
	v_mfma_f32_16x16x32_bf16 v[6:9], v[78:81], v[234:237], v[6:9]
	v_mfma_f32_16x16x32_bf16 v[2:5], v[86:89], v[234:237], v[2:5]
	v_mfma_f32_16x16x32_bf16 v[58:61], v[98:101], v[162:165], v[58:61]
	v_mfma_f32_16x16x32_bf16 v[50:53], v[106:109], v[162:165], v[50:53]
	v_mfma_f32_16x16x32_bf16 v[42:45], v[98:101], v[170:173], v[42:45]
	v_mfma_f32_16x16x32_bf16 v[34:37], v[106:109], v[170:173], v[34:37]
	v_mfma_f32_16x16x32_bf16 v[26:29], v[98:101], v[194:197], v[26:29]
	v_mfma_f32_16x16x32_bf16 v[18:21], v[106:109], v[194:197], v[18:21]
	v_mfma_f32_16x16x32_bf16 v[14:17], v[98:101], v[230:233], v[14:17]
	v_mfma_f32_16x16x32_bf16 v[10:13], v[106:109], v[230:233], v[10:13]
	v_mfma_f32_16x16x32_bf16 v[58:61], v[102:105], v[166:169], v[58:61]
	v_mfma_f32_16x16x32_bf16 v[50:53], v[110:113], v[166:169], v[50:53]
	v_mfma_f32_16x16x32_bf16 v[42:45], v[102:105], v[174:177], v[42:45]
	v_mfma_f32_16x16x32_bf16 v[34:37], v[110:113], v[174:177], v[34:37]
	v_mfma_f32_16x16x32_bf16 v[26:29], v[102:105], v[220:223], v[26:29]
	v_mfma_f32_16x16x32_bf16 v[18:21], v[110:113], v[220:223], v[18:21]
	v_mfma_f32_16x16x32_bf16 v[14:17], v[102:105], v[234:237], v[14:17]
	v_mfma_f32_16x16x32_bf16 v[10:13], v[110:113], v[234:237], v[10:13]
	s_setprio 0
	s_barrier
	s_add_u32 s9, s9, 0x100
	s_addc_u32 s34, s34, 0
	s_add_u32 s4, s4, 0x100
	s_addc_u32 s5, s5, 0
	s_cmp_ge_i32 s35, s76
	s_mov_b32 s6, s35
	s_cbranch_scc0 .LBB0_1274

.LBB0_1401:
	v_add_u32_e32 v0, s63, v142
	ds_read_b128 v[144:147], v0
	ds_read_b128 v[148:151], v0 offset:1024
	ds_read_b128 v[152:155], v0 offset:2048
	ds_read_b128 v[156:159], v0 offset:3072
	v_add_u32_e32 v0, s66, v142
	ds_read_b128 v[160:163], v0
	ds_read_b128 v[164:167], v0 offset:1024
	ds_read_b128 v[168:171], v0 offset:2048
	ds_read_b128 v[182:185], v0 offset:3072
	s_add_i32 s89, s34, 2
	s_add_u32 s90, s30, 0x80
	s_addc_u32 s35, s31, 0
	s_cmp_eq_u32 s82, s34
	s_cselect_b32 s34, s0, s90
	s_cselect_b32 s35, s1, s35
	s_cselect_b32 s91, s29, s88
	s_cselect_b32 s90, s28, s87
	v_lshl_add_u64 v[176:177], s[30:31], 0, v[140:141]
	s_add_i32 m0, s69, 0xc000
	ds_read_b128 v[186:189], v143
	ds_read_b128 v[190:193], v143 offset:1024
	ds_read_b128 v[194:197], v143 offset:2048
	ds_read_b128 v[218:221], v143 offset:3072
	ds_read_b128 v[222:225], v143 offset:4096
	ds_read_b128 v[230:233], v143 offset:5120
	ds_read_b128 v[234:237], v143 offset:6144
	ds_read_b128 v[238:241], v143 offset:7168
	global_load_lds_dwordx4 v[176:177], off
	v_lshl_add_u64 v[176:177], s[30:31], 0, v[138:139]
	s_add_i32 m0, s69, 0xe000
	s_nop 0
	global_load_lds_dwordx4 v[176:177], off
	s_waitcnt vmcnt(8)
	s_waitcnt lgkmcnt(0)
	s_barrier
	s_setprio 1
	s_waitcnt lgkmcnt(0)
	v_mfma_f32_16x16x32_bf16 v[2:5], v[144:147], v[186:189], v[2:5]
	v_mfma_f32_16x16x32_bf16 v[42:45], v[152:155], v[186:189], v[42:45]
	v_mfma_f32_16x16x32_bf16 v[86:89], v[144:147], v[194:197], v[86:89]
	v_mfma_f32_16x16x32_bf16 v[54:57], v[152:155], v[194:197], v[54:57]
	v_mfma_f32_16x16x32_bf16 v[94:97], v[144:147], v[222:225], v[94:97]
	v_mfma_f32_16x16x32_bf16 v[62:65], v[152:155], v[222:225], v[62:65]
	v_mfma_f32_16x16x32_bf16 v[98:101], v[144:147], v[234:237], v[98:101]
	v_mfma_f32_16x16x32_bf16 v[66:69], v[152:155], v[234:237], v[66:69]
	v_mfma_f32_16x16x32_bf16 v[2:5], v[148:151], v[190:193], v[2:5]
	v_mfma_f32_16x16x32_bf16 v[42:45], v[156:159], v[190:193], v[42:45]
	v_mfma_f32_16x16x32_bf16 v[86:89], v[148:151], v[218:221], v[86:89]
	v_mfma_f32_16x16x32_bf16 v[54:57], v[156:159], v[218:221], v[54:57]
	v_mfma_f32_16x16x32_bf16 v[94:97], v[148:151], v[230:233], v[94:97]
	v_mfma_f32_16x16x32_bf16 v[62:65], v[156:159], v[230:233], v[62:65]
	v_mfma_f32_16x16x32_bf16 v[98:101], v[148:151], v[238:241], v[98:101]
	v_mfma_f32_16x16x32_bf16 v[66:69], v[156:159], v[238:241], v[66:69]
	v_mfma_f32_16x16x32_bf16 v[18:21], v[160:163], v[186:189], v[18:21]
	v_mfma_f32_16x16x32_bf16 v[130:133], v[168:171], v[186:189], v[130:133]
	v_mfma_f32_16x16x32_bf16 v[26:29], v[160:163], v[194:197], v[26:29]
	v_mfma_f32_16x16x32_bf16 v[6:9], v[168:171], v[194:197], v[6:9]
	v_mfma_f32_16x16x32_bf16 v[34:37], v[160:163], v[222:225], v[34:37]
	v_mfma_f32_16x16x32_bf16 v[10:13], v[168:171], v[222:225], v[10:13]
	v_mfma_f32_16x16x32_bf16 v[38:41], v[160:163], v[234:237], v[38:41]
	v_mfma_f32_16x16x32_bf16 v[14:17], v[168:171], v[234:237], v[14:17]
	v_mfma_f32_16x16x32_bf16 v[18:21], v[164:167], v[190:193], v[18:21]
	v_mfma_f32_16x16x32_bf16 v[130:133], v[182:185], v[190:193], v[130:133]
	v_mfma_f32_16x16x32_bf16 v[26:29], v[164:167], v[218:221], v[26:29]
	v_mfma_f32_16x16x32_bf16 v[6:9], v[182:185], v[218:221], v[6:9]
	v_mfma_f32_16x16x32_bf16 v[34:37], v[164:167], v[230:233], v[34:37]
	v_mfma_f32_16x16x32_bf16 v[10:13], v[182:185], v[230:233], v[10:13]
	v_mfma_f32_16x16x32_bf16 v[38:41], v[164:167], v[238:241], v[38:41]
	v_mfma_f32_16x16x32_bf16 v[14:17], v[182:185], v[238:241], v[14:17]
	s_setprio 0
	s_barrier
	s_mov_b32 m0, s64
	v_lshl_add_u64 v[176:177], s[90:91], 0, v[134:135]
	v_lshl_add_u64 v[198:199], s[90:91], 0, v[74:75]
	s_add_u32 s90, s90, s12
	ds_read_b128 v[186:189], v143 offset:16384
	ds_read_b128 v[190:193], v143 offset:17408
	ds_read_b128 v[194:197], v143 offset:18432
	ds_read_b128 v[218:221], v143 offset:19456
	ds_read_b128 v[222:225], v143 offset:20480
	ds_read_b128 v[230:233], v143 offset:21504
	ds_read_b128 v[234:237], v143 offset:22528
	ds_read_b128 v[238:241], v143 offset:23552
	global_load_lds_dwordx4 v[176:177], off
	s_mov_b32 m0, s65
	s_addc_u32 s91, s91, s13
	global_load_lds_dwordx4 v[198:199], off
	v_lshl_add_u64 v[242:243], s[90:91], 0, v[134:135]
	s_mov_b32 m0, s67
	v_lshl_add_u64 v[244:245], s[90:91], 0, v[74:75]
	global_load_lds_dwordx4 v[242:243], off
	s_mov_b32 m0, s68
	v_lshl_add_u64 v[246:247], s[34:35], 0, v[136:137]
	global_load_lds_dwordx4 v[244:245], off
	s_mov_b32 m0, s69
	v_lshl_add_u64 v[248:249], s[34:35], 0, v[76:77]
	global_load_lds_dwordx4 v[246:247], off
	s_mov_b32 m0, s70
	s_nop 0
	global_load_lds_dwordx4 v[248:249], off
	s_waitcnt vmcnt(8)
	s_waitcnt lgkmcnt(0)
	s_barrier
	s_setprio 1
	s_waitcnt lgkmcnt(0)
	v_mfma_f32_16x16x32_bf16 v[102:105], v[144:147], v[186:189], v[102:105]
	v_mfma_f32_16x16x32_bf16 v[70:73], v[152:155], v[186:189], v[70:73]
	v_mfma_f32_16x16x32_bf16 v[114:117], v[144:147], v[194:197], v[114:117]
	v_mfma_f32_16x16x32_bf16 v[90:93], v[152:155], v[194:197], v[90:93]
	v_mfma_f32_16x16x32_bf16 v[126:129], v[144:147], v[222:225], v[126:129]
	v_mfma_f32_16x16x32_bf16 v[110:113], v[152:155], v[222:225], v[110:113]
	v_mfma_f32_16x16x32_bf16 v[122:125], v[144:147], v[234:237], v[122:125]
	v_mfma_f32_16x16x32_bf16 v[118:121], v[152:155], v[234:237], v[118:121]
	v_mfma_f32_16x16x32_bf16 v[102:105], v[148:151], v[190:193], v[102:105]
	v_mfma_f32_16x16x32_bf16 v[70:73], v[156:159], v[190:193], v[70:73]
	v_mfma_f32_16x16x32_bf16 v[114:117], v[148:151], v[218:221], v[114:117]
	v_mfma_f32_16x16x32_bf16 v[90:93], v[156:159], v[218:221], v[90:93]
	v_mfma_f32_16x16x32_bf16 v[126:129], v[148:151], v[230:233], v[126:129]
	v_mfma_f32_16x16x32_bf16 v[110:113], v[156:159], v[230:233], v[110:113]
	v_mfma_f32_16x16x32_bf16 v[122:125], v[148:151], v[238:241], v[122:125]
	v_mfma_f32_16x16x32_bf16 v[118:121], v[156:159], v[238:241], v[118:121]
	v_mfma_f32_16x16x32_bf16 v[46:49], v[160:163], v[186:189], v[46:49]
	v_mfma_f32_16x16x32_bf16 v[22:25], v[168:171], v[186:189], v[22:25]
	v_mfma_f32_16x16x32_bf16 v[58:61], v[160:163], v[194:197], v[58:61]
	v_mfma_f32_16x16x32_bf16 v[30:33], v[168:171], v[194:197], v[30:33]
	v_mfma_f32_16x16x32_bf16 v[82:85], v[160:163], v[222:225], v[82:85]
	v_mfma_f32_16x16x32_bf16 v[50:53], v[168:171], v[222:225], v[50:53]
	v_mfma_f32_16x16x32_bf16 v[106:109], v[160:163], v[234:237], v[106:109]
	v_mfma_f32_16x16x32_bf16 v[78:81], v[168:171], v[234:237], v[78:81]
	v_mfma_f32_16x16x32_bf16 v[46:49], v[164:167], v[190:193], v[46:49]
	v_mfma_f32_16x16x32_bf16 v[22:25], v[182:185], v[190:193], v[22:25]
	v_mfma_f32_16x16x32_bf16 v[58:61], v[164:167], v[218:221], v[58:61]
	v_mfma_f32_16x16x32_bf16 v[30:33], v[182:185], v[218:221], v[30:33]
	v_mfma_f32_16x16x32_bf16 v[82:85], v[164:167], v[230:233], v[82:85]
	v_mfma_f32_16x16x32_bf16 v[50:53], v[182:185], v[230:233], v[50:53]
	v_mfma_f32_16x16x32_bf16 v[106:109], v[164:167], v[238:241], v[106:109]
	v_mfma_f32_16x16x32_bf16 v[78:81], v[182:185], v[238:241], v[78:81]
	s_setprio 0
	s_barrier
	v_add_u32_e32 v0, s73, v142
	ds_read_b128 v[144:147], v0
	ds_read_b128 v[148:151], v0 offset:1024
	ds_read_b128 v[152:155], v0 offset:2048
	ds_read_b128 v[156:159], v0 offset:3072
	v_add_u32_e32 v0, s78, v142
	ds_read_b128 v[160:163], v0
	ds_read_b128 v[164:167], v0 offset:1024
	ds_read_b128 v[168:171], v0 offset:2048
	ds_read_b128 v[182:185], v0 offset:3072
	s_add_u32 s34, s34, s10
	s_addc_u32 s35, s35, s11
	s_mov_b32 m0, s71
	v_lshl_add_u64 v[250:251], s[34:35], 0, v[136:137]
	ds_read_b128 v[186:189], v143 offset:32768
	ds_read_b128 v[190:193], v143 offset:33792
	ds_read_b128 v[194:197], v143 offset:34816
	ds_read_b128 v[218:221], v143 offset:35840
	ds_read_b128 v[222:225], v143 offset:36864
	ds_read_b128 v[230:233], v143 offset:37888
	ds_read_b128 v[234:237], v143 offset:38912
	ds_read_b128 v[238:241], v143 offset:39936
	global_load_lds_dwordx4 v[250:251], off
	v_lshl_add_u64 v[250:251], s[34:35], 0, v[76:77]
	s_mov_b32 m0, s72
	s_nop 0
	global_load_lds_dwordx4 v[250:251], off
	s_waitcnt vmcnt(8)
	s_waitcnt lgkmcnt(0)
	s_barrier
	s_setprio 1
	s_waitcnt lgkmcnt(0)
	v_mfma_f32_16x16x32_bf16 v[2:5], v[144:147], v[186:189], v[2:5]
	v_mfma_f32_16x16x32_bf16 v[42:45], v[152:155], v[186:189], v[42:45]
	v_mfma_f32_16x16x32_bf16 v[86:89], v[144:147], v[194:197], v[86:89]
	v_mfma_f32_16x16x32_bf16 v[54:57], v[152:155], v[194:197], v[54:57]
	v_mfma_f32_16x16x32_bf16 v[94:97], v[144:147], v[222:225], v[94:97]
	v_mfma_f32_16x16x32_bf16 v[62:65], v[152:155], v[222:225], v[62:65]
	v_mfma_f32_16x16x32_bf16 v[98:101], v[144:147], v[234:237], v[98:101]
	v_mfma_f32_16x16x32_bf16 v[66:69], v[152:155], v[234:237], v[66:69]
	v_mfma_f32_16x16x32_bf16 v[2:5], v[148:151], v[190:193], v[2:5]
	v_mfma_f32_16x16x32_bf16 v[42:45], v[156:159], v[190:193], v[42:45]
	v_mfma_f32_16x16x32_bf16 v[86:89], v[148:151], v[218:221], v[86:89]
	v_mfma_f32_16x16x32_bf16 v[54:57], v[156:159], v[218:221], v[54:57]
	v_mfma_f32_16x16x32_bf16 v[94:97], v[148:151], v[230:233], v[94:97]
	v_mfma_f32_16x16x32_bf16 v[62:65], v[156:159], v[230:233], v[62:65]
	v_mfma_f32_16x16x32_bf16 v[98:101], v[148:151], v[238:241], v[98:101]
	v_mfma_f32_16x16x32_bf16 v[66:69], v[156:159], v[238:241], v[66:69]
	v_mfma_f32_16x16x32_bf16 v[18:21], v[160:163], v[186:189], v[18:21]
	v_mfma_f32_16x16x32_bf16 v[130:133], v[168:171], v[186:189], v[130:133]
	v_mfma_f32_16x16x32_bf16 v[26:29], v[160:163], v[194:197], v[26:29]
	v_mfma_f32_16x16x32_bf16 v[6:9], v[168:171], v[194:197], v[6:9]
	v_mfma_f32_16x16x32_bf16 v[34:37], v[160:163], v[222:225], v[34:37]
	v_mfma_f32_16x16x32_bf16 v[10:13], v[168:171], v[222:225], v[10:13]
	v_mfma_f32_16x16x32_bf16 v[38:41], v[160:163], v[234:237], v[38:41]
	v_mfma_f32_16x16x32_bf16 v[14:17], v[168:171], v[234:237], v[14:17]
	v_mfma_f32_16x16x32_bf16 v[18:21], v[164:167], v[190:193], v[18:21]
	v_mfma_f32_16x16x32_bf16 v[130:133], v[182:185], v[190:193], v[130:133]
	v_mfma_f32_16x16x32_bf16 v[26:29], v[164:167], v[218:221], v[26:29]
	v_mfma_f32_16x16x32_bf16 v[6:9], v[182:185], v[218:221], v[6:9]
	v_mfma_f32_16x16x32_bf16 v[34:37], v[164:167], v[230:233], v[34:37]
	v_mfma_f32_16x16x32_bf16 v[10:13], v[182:185], v[230:233], v[10:13]
	v_mfma_f32_16x16x32_bf16 v[38:41], v[164:167], v[238:241], v[38:41]
	v_mfma_f32_16x16x32_bf16 v[14:17], v[182:185], v[238:241], v[14:17]
	s_setprio 0
	s_barrier
	s_mov_b32 m0, s74
	v_lshl_add_u64 v[176:177], v[176:177], 0, s[48:49]
	ds_read_b128 v[186:189], v143 offset:49152
	ds_read_b128 v[190:193], v143 offset:50176
	ds_read_b128 v[194:197], v143 offset:51200
	ds_read_b128 v[218:221], v143 offset:52224
	ds_read_b128 v[222:225], v143 offset:53248
	ds_read_b128 v[230:233], v143 offset:54272
	ds_read_b128 v[234:237], v143 offset:55296
	ds_read_b128 v[238:241], v143 offset:56320
	global_load_lds_dwordx4 v[176:177], off
	v_lshl_add_u64 v[176:177], v[198:199], 0, s[48:49]
	s_mov_b32 m0, s75
	s_nop 0
	global_load_lds_dwordx4 v[176:177], off
	v_lshl_add_u64 v[176:177], v[242:243], 0, s[48:49]
	s_mov_b32 m0, s79
	s_nop 0
	global_load_lds_dwordx4 v[176:177], off
	v_lshl_add_u64 v[176:177], v[244:245], 0, s[48:49]
	s_mov_b32 m0, s80
	s_nop 0
	global_load_lds_dwordx4 v[176:177], off
	v_lshl_add_u64 v[176:177], v[246:247], 0, s[48:49]
	s_mov_b32 m0, s76
	s_nop 0
	global_load_lds_dwordx4 v[176:177], off
	v_lshl_add_u64 v[176:177], v[248:249], 0, s[48:49]
	s_mov_b32 m0, s77
	s_nop 0
	global_load_lds_dwordx4 v[176:177], off
	s_waitcnt vmcnt(8)
	s_waitcnt lgkmcnt(0)
	s_barrier
	s_setprio 1
	s_waitcnt lgkmcnt(0)
	v_mfma_f32_16x16x32_bf16 v[102:105], v[144:147], v[186:189], v[102:105]
	v_mfma_f32_16x16x32_bf16 v[70:73], v[152:155], v[186:189], v[70:73]
	v_mfma_f32_16x16x32_bf16 v[114:117], v[144:147], v[194:197], v[114:117]
	v_mfma_f32_16x16x32_bf16 v[90:93], v[152:155], v[194:197], v[90:93]
	v_mfma_f32_16x16x32_bf16 v[126:129], v[144:147], v[222:225], v[126:129]
	v_mfma_f32_16x16x32_bf16 v[110:113], v[152:155], v[222:225], v[110:113]
	v_mfma_f32_16x16x32_bf16 v[122:125], v[144:147], v[234:237], v[122:125]
	v_mfma_f32_16x16x32_bf16 v[118:121], v[152:155], v[234:237], v[118:121]
	v_mfma_f32_16x16x32_bf16 v[102:105], v[148:151], v[190:193], v[102:105]
	v_mfma_f32_16x16x32_bf16 v[70:73], v[156:159], v[190:193], v[70:73]
	v_mfma_f32_16x16x32_bf16 v[114:117], v[148:151], v[218:221], v[114:117]
	v_mfma_f32_16x16x32_bf16 v[90:93], v[156:159], v[218:221], v[90:93]
	v_mfma_f32_16x16x32_bf16 v[126:129], v[148:151], v[230:233], v[126:129]
	v_mfma_f32_16x16x32_bf16 v[110:113], v[156:159], v[230:233], v[110:113]
	v_mfma_f32_16x16x32_bf16 v[122:125], v[148:151], v[238:241], v[122:125]
	v_mfma_f32_16x16x32_bf16 v[118:121], v[156:159], v[238:241], v[118:121]
	v_mfma_f32_16x16x32_bf16 v[46:49], v[160:163], v[186:189], v[46:49]
	v_mfma_f32_16x16x32_bf16 v[22:25], v[168:171], v[186:189], v[22:25]
	v_mfma_f32_16x16x32_bf16 v[58:61], v[160:163], v[194:197], v[58:61]
	v_mfma_f32_16x16x32_bf16 v[30:33], v[168:171], v[194:197], v[30:33]
	v_mfma_f32_16x16x32_bf16 v[82:85], v[160:163], v[222:225], v[82:85]
	v_mfma_f32_16x16x32_bf16 v[50:53], v[168:171], v[222:225], v[50:53]
	v_mfma_f32_16x16x32_bf16 v[106:109], v[160:163], v[234:237], v[106:109]
	v_mfma_f32_16x16x32_bf16 v[78:81], v[168:171], v[234:237], v[78:81]
	v_mfma_f32_16x16x32_bf16 v[46:49], v[164:167], v[190:193], v[46:49]
	v_mfma_f32_16x16x32_bf16 v[22:25], v[182:185], v[190:193], v[22:25]
	v_mfma_f32_16x16x32_bf16 v[58:61], v[164:167], v[218:221], v[58:61]
	v_mfma_f32_16x16x32_bf16 v[30:33], v[182:185], v[218:221], v[30:33]
	v_mfma_f32_16x16x32_bf16 v[82:85], v[164:167], v[230:233], v[82:85]
	v_mfma_f32_16x16x32_bf16 v[50:53], v[182:185], v[230:233], v[50:53]
	v_mfma_f32_16x16x32_bf16 v[106:109], v[164:167], v[238:241], v[106:109]
	v_mfma_f32_16x16x32_bf16 v[78:81], v[182:185], v[238:241], v[78:81]
	s_setprio 0
	s_barrier
	s_add_u32 s87, s87, 0x100
	s_addc_u32 s88, s88, 0
	s_add_u32 s30, s30, 0x100
	s_addc_u32 s31, s31, 0
	s_cmp_ge_i32 s89, s81
	s_mov_b32 s34, s89
	s_cbranch_scc0 .LBB0_1401
	v_readlane_b32 s88, v252, 7
	v_readlane_b32 s89, v252, 8
	s_and_b64 vcc, exec, s[4:5]
	s_cbranch_vccnz .LBB0_1394
	s_branch .LBB0_1406
